# speedup vs baseline: 1.0135x; 1.0007x over previous
; #define WAIT_V0() asm volatile("s_waitcnt vmcnt(0)" ::: "memory")
; #define WAIT_L0() asm volatile("s_waitcnt lgkmcnt(0)" ::: "memory")
; __device__ __forceinline__ void ph_indexer(const Params& p, char* shm) {
;     ...
;       h16x2 wq[2][8];
;       IDX_STAGE(0, 0);
;       for (int st = 0; st < nst; ++st) {
;         if (st == 0) WAIT_V0(); else asm volatile("s_waitcnt vmcnt(4)" ::: "memory");
;         WAIT_L0();
;         __builtin_amdgcn_s_barrier();
;         if (st + 1 < nst) IDX_STAGE((st + 1) & 1, st + 1);
;         if (st == 0) {
; #pragma unroll
;           for (int q = 0; q < 2; ++q)
; #pragma unroll
;             for (int i4 = 0; i4 < 4; ++i4) {
;               const uint2 u = *(const uint2*)(wtab + (wid * 2 + q) * 64 + (half * 4 + 8 * i4) * 2);
;               wq[q][2 * i4] = __builtin_bit_cast(h16x2, u.x);
;               wq[q][2 * i4 + 1] = __builtin_bit_cast(h16x2, u.y);
;             }
;         }
;         const char* kbuf = shm + (st & 1) * 32768;
; #pragma unroll 1
;         for (int ktp = 0; ktp < 2; ++ktp) {
;           float pr0[2], pr1[2];
;     ...
;           IDX_TILE(ktp * 2, pr0);
.LBB0_924:
	s_waitcnt lgkmcnt(0)
	s_add_i32 s22, s4, 1
	s_cmp_ge_u32 s22, s44
	s_barrier
.LBB0_926:
	s_andn2_b64 vcc, exec, s[20:21]
	s_cbranch_vccnz .LBB0_928
	v_lshrrev_b32_e32 v0, 1, v204
	v_and_b32_e32 v0, 24, v0
	v_add_u32_e32 v0, s27, v0
	s_waitcnt vmcnt(0)
	ds_read2_b64 v[34:37], v0 offset1:4
	ds_read2_b64 v[38:41], v0 offset0:8 offset1:12
.LBB0_928:
	s_lshl_b32 s3, s4, 15
	v_cmp_lt_i32_e32 vcc, v209, v208
	s_and_b32 s3, s3, 0x8000
	s_lshl_b32 s4, s4, 7
	v_cndmask_b32_e32 v0, v207, v209, vcc
	v_or_b32_e32 v129, s3, v117
	v_lshlrev_b32_e32 v119, 2, v0
	v_lshl_add_u64 v[138:139], s[4:5], 2, v[124:125]
	ds_read_b128 v[172:175], v129
	ds_read_b128 v[176:179], v129 offset:256
	ds_read_b128 v[180:183], v129 offset:2048
	ds_read_b128 v[184:187], v129 offset:2304
	ds_read_b128 v[188:191], v129 offset:4096
	ds_read_b128 v[192:195], v129 offset:4352
	ds_read_b128 v[196:199], v129 offset:6144
	ds_read_b128 v[226:229], v129 offset:6400
	v_lshl_add_u64 v[232:233], v[138:139], 0, s[16:17]
	v_lshl_add_u64 v[234:235], v[138:139], 0, s[18:19]
	s_waitcnt lgkmcnt(8)
	v_cvt_f32_f16_e32 v140, v34
	v_cvt_f32_f16_sdwa v141, v34 dst_sel:DWORD dst_unused:UNUSED_PAD src0_sel:WORD_1
	v_cvt_f32_f16_e32 v142, v35
	v_cvt_f32_f16_sdwa v143, v35 dst_sel:DWORD dst_unused:UNUSED_PAD src0_sel:WORD_1
	v_cvt_f32_f16_e32 v144, v36
	v_cvt_f32_f16_sdwa v145, v36 dst_sel:DWORD dst_unused:UNUSED_PAD src0_sel:WORD_1
	v_cvt_f32_f16_e32 v146, v37
	v_cvt_f32_f16_sdwa v147, v37 dst_sel:DWORD dst_unused:UNUSED_PAD src0_sel:WORD_1
	v_cvt_f32_f16_e32 v148, v38
	v_cvt_f32_f16_sdwa v149, v38 dst_sel:DWORD dst_unused:UNUSED_PAD src0_sel:WORD_1
	v_cvt_f32_f16_e32 v150, v39
	v_cvt_f32_f16_sdwa v151, v39 dst_sel:DWORD dst_unused:UNUSED_PAD src0_sel:WORD_1
	v_cvt_f32_f16_e32 v152, v40
	v_cvt_f32_f16_sdwa v153, v40 dst_sel:DWORD dst_unused:UNUSED_PAD src0_sel:WORD_1
	v_cvt_f32_f16_e32 v154, v41
	v_cvt_f32_f16_sdwa v155, v41 dst_sel:DWORD dst_unused:UNUSED_PAD src0_sel:WORD_1
	s_waitcnt lgkmcnt(7)
	v_mfma_f32_16x16x32_bf16 v[0:3], v[74:77], v[172:175], 0
	v_mfma_f32_16x16x32_bf16 v[8:11], v[62:65], v[172:175], 0
	s_waitcnt lgkmcnt(6)
	v_mfma_f32_16x16x32_bf16 v[4:7], v[74:77], v[176:179], 0
	v_mfma_f32_16x16x32_bf16 v[12:15], v[62:65], v[176:179], 0
	s_waitcnt lgkmcnt(5)
	v_mfma_f32_16x16x32_bf16 v[0:3], v[50:53], v[180:183], v[0:3]
	v_mfma_f32_16x16x32_bf16 v[8:11], v[66:69], v[180:183], v[8:11]
	s_waitcnt lgkmcnt(4)
	v_mfma_f32_16x16x32_bf16 v[4:7], v[50:53], v[184:187], v[4:7]
	v_mfma_f32_16x16x32_bf16 v[12:15], v[66:69], v[184:187], v[12:15]
	s_waitcnt lgkmcnt(3)
	v_mfma_f32_16x16x32_bf16 v[0:3], v[54:57], v[188:191], v[0:3]
	v_mfma_f32_16x16x32_bf16 v[8:11], v[70:73], v[188:191], v[8:11]
	s_waitcnt lgkmcnt(2)
	v_mfma_f32_16x16x32_bf16 v[4:7], v[54:57], v[192:195], v[4:7]
	v_mfma_f32_16x16x32_bf16 v[12:15], v[70:73], v[192:195], v[12:15]
	s_waitcnt lgkmcnt(1)
	v_mfma_f32_16x16x32_bf16 v[0:3], v[58:61], v[196:199], v[0:3]
	v_mfma_f32_16x16x32_bf16 v[8:11], v[78:81], v[196:199], v[8:11]
	s_waitcnt lgkmcnt(0)
	v_mfma_f32_16x16x32_bf16 v[4:7], v[58:61], v[226:229], v[4:7]
	v_mfma_f32_16x16x32_bf16 v[12:15], v[78:81], v[226:229], v[12:15]
	v_mfma_f32_16x16x32_bf16 v[16:19], v[106:109], v[172:175], 0
	v_mfma_f32_16x16x32_bf16 v[24:27], v[94:97], v[172:175], 0
	ds_read_b128 v[172:175], v129 offset:8192
	v_mfma_f32_16x16x32_bf16 v[20:23], v[106:109], v[176:179], 0
	s_cmp_ge_u32 s22, s44
	s_cbranch_scc1 .Lidx_nostage_s0_0
	v_lshl_add_u32 v236, s22, 7, v118
	v_ashrrev_i32_e32 v237, 31, v236
	s_lshl_b32 s3, s22, 15
	v_lshlrev_b64 v[236:237], 8, v[236:237]
	s_and_b32 s3, s3, 0x8000
	v_lshl_add_u64 v[236:237], v[126:127], 0, v[236:237]
	s_add_i32 s23, s26, s3
	s_mov_b32 s3, s5
	v_lshl_add_u64 v[238:239], v[236:237], 0, s[2:3]
	s_add_i32 m0, s23, s29
	s_mov_b32 s9, s5
	global_load_lds_dwordx4 v[238:239], off
.Lidx_nostage_s0_0:
	v_mfma_f32_16x16x32_bf16 v[28:31], v[94:97], v[176:179], 0
	ds_read_b128 v[176:179], v129 offset:8448
	s_cmp_ge_u32 s22, s44
	s_cbranch_scc1 .Lidx_nostage_s0_1
	v_lshl_add_u64 v[238:239], v[236:237], 0, s[8:9]
	s_add_i32 m0, s23, s31
	s_mov_b32 s11, s5
	global_load_lds_dwordx4 v[238:239], off
.Lidx_nostage_s0_1:
	v_mfma_f32_16x16x32_bf16 v[16:19], v[82:85], v[180:183], v[16:19]
	s_cmp_ge_u32 s22, s44
	s_cbranch_scc1 .Lidx_nostage_s0_2
	v_lshl_add_u64 v[238:239], v[236:237], 0, s[10:11]
	s_add_i32 m0, s23, s35
	s_mov_b32 s13, s5
	global_load_lds_dwordx4 v[238:239], off
.Lidx_nostage_s0_2:
	v_max_i32_e32 v224, 0, v0
	v_fma_f32 v200, v224, v140, 0
	v_mfma_f32_16x16x32_bf16 v[24:27], v[98:101], v[180:183], v[24:27]
	ds_read_b128 v[180:183], v129 offset:10240
	s_cmp_ge_u32 s22, s44
	s_cbranch_scc1 .Lidx_nostage_s0_3
	v_lshl_add_u64 v[236:237], v[236:237], 0, s[12:13]
	s_add_i32 m0, s23, s37
	s_nop 0
	global_load_lds_dwordx4 v[236:237], off
; __device__ __forceinline__ void ph_indexer(const Params& p, char* shm) {
;     ...
;           IDX_TILE(ktp * 2, pr0);
;           __builtin_amdgcn_sched_barrier(0);
;           IDX_TILE(ktp * 2 + 1, pr1);
;           __builtin_amdgcn_sched_barrier(0);
;     ...
; #pragma unroll
;           for (int q = 0; q < 2; ++q) {
;             const float mine = half ? pr1[q] : pr0[q];
;             const float send = half ? pr0[q] : pr1[q];
;             const float recv = __shfl_xor(send, 32);
;             p.SC[(rowb + wid * 2 + q) * L + st * 128 + ktp * 64 + lane] = mine + recv;
;           }
.Lidx_nostage_s0_3:
	v_max_i32_e32 v225, 0, v1
	v_fmac_f32_e32 v200, v225, v141
	v_mfma_f32_16x16x32_bf16 v[20:23], v[82:85], v[184:187], v[20:23]
	v_max_i32_e32 v224, 0, v2
	v_fmac_f32_e32 v200, v224, v142
	v_max_i32_e32 v225, 0, v3
	v_mfma_f32_16x16x32_bf16 v[28:31], v[98:101], v[184:187], v[28:31]
	ds_read_b128 v[184:187], v129 offset:10496
	v_fmac_f32_e32 v200, v225, v143
	v_max_i32_e32 v224, 0, v8
	v_fmac_f32_e32 v200, v224, v144
	v_mfma_f32_16x16x32_bf16 v[16:19], v[86:89], v[188:191], v[16:19]
	v_max_i32_e32 v225, 0, v9
	v_fmac_f32_e32 v200, v225, v145
	v_max_i32_e32 v224, 0, v10
	v_mfma_f32_16x16x32_bf16 v[24:27], v[102:105], v[188:191], v[24:27]
	ds_read_b128 v[188:191], v129 offset:12288
	v_fmac_f32_e32 v200, v224, v146
	v_max_i32_e32 v225, 0, v11
	v_fmac_f32_e32 v200, v225, v147
	v_mfma_f32_16x16x32_bf16 v[20:23], v[86:89], v[192:195], v[20:23]
	v_max_i32_e32 v224, 0, v4
	v_fma_f32 v201, v224, v140, 0
	v_max_i32_e32 v225, 0, v5
	v_mfma_f32_16x16x32_bf16 v[28:31], v[102:105], v[192:195], v[28:31]
	ds_read_b128 v[192:195], v129 offset:12544
	v_fmac_f32_e32 v201, v225, v141
	v_max_i32_e32 v224, 0, v6
	v_fmac_f32_e32 v201, v224, v142
	v_mfma_f32_16x16x32_bf16 v[16:19], v[90:93], v[196:199], v[16:19]
	v_max_i32_e32 v225, 0, v7
	v_fmac_f32_e32 v201, v225, v143
	v_max_i32_e32 v224, 0, v12
	v_mfma_f32_16x16x32_bf16 v[24:27], v[110:113], v[196:199], v[24:27]
	ds_read_b128 v[196:199], v129 offset:14336
	v_fmac_f32_e32 v201, v224, v144
	v_max_i32_e32 v225, 0, v13
	v_fmac_f32_e32 v201, v225, v145
	v_mfma_f32_16x16x32_bf16 v[20:23], v[90:93], v[226:229], v[20:23]
	v_max_i32_e32 v224, 0, v14
	v_fmac_f32_e32 v201, v224, v146
	v_mfma_f32_16x16x32_bf16 v[28:31], v[110:113], v[226:229], v[28:31]
	ds_read_b128 v[226:229], v129 offset:14592
	v_max_i32_e32 v225, 0, v15
	v_fmac_f32_e32 v201, v225, v147
	s_waitcnt lgkmcnt(7)
	v_mfma_f32_16x16x32_bf16 v[0:3], v[74:77], v[172:175], 0
	v_mfma_f32_16x16x32_bf16 v[8:11], v[62:65], v[172:175], 0
	s_waitcnt lgkmcnt(6)
	v_mfma_f32_16x16x32_bf16 v[4:7], v[74:77], v[176:179], 0
	v_mfma_f32_16x16x32_bf16 v[12:15], v[62:65], v[176:179], 0
	v_max_i32_e32 v230, 0, v16
	v_fma_f32 v202, v230, v148, 0
	s_waitcnt lgkmcnt(5)
	v_mfma_f32_16x16x32_bf16 v[0:3], v[50:53], v[180:183], v[0:3]
	v_max_i32_e32 v231, 0, v17
	v_fmac_f32_e32 v202, v231, v149
	v_mfma_f32_16x16x32_bf16 v[8:11], v[66:69], v[180:183], v[8:11]
	v_max_i32_e32 v230, 0, v18
	v_fmac_f32_e32 v202, v230, v150
	s_waitcnt lgkmcnt(4)
	v_mfma_f32_16x16x32_bf16 v[4:7], v[50:53], v[184:187], v[4:7]
	v_max_i32_e32 v231, 0, v19
	v_fmac_f32_e32 v202, v231, v151
	v_mfma_f32_16x16x32_bf16 v[12:15], v[66:69], v[184:187], v[12:15]
	v_max_i32_e32 v230, 0, v24
	v_fmac_f32_e32 v202, v230, v152
	s_waitcnt lgkmcnt(3)
	v_mfma_f32_16x16x32_bf16 v[0:3], v[54:57], v[188:191], v[0:3]
	v_max_i32_e32 v231, 0, v25
	v_fmac_f32_e32 v202, v231, v153
	v_mfma_f32_16x16x32_bf16 v[8:11], v[70:73], v[188:191], v[8:11]
	v_max_i32_e32 v230, 0, v26
	v_fmac_f32_e32 v202, v230, v154
	v_max_i32_e32 v231, 0, v27
	s_waitcnt lgkmcnt(2)
	v_mfma_f32_16x16x32_bf16 v[4:7], v[54:57], v[192:195], v[4:7]
	v_fmac_f32_e32 v202, v231, v155
	v_max_i32_e32 v230, 0, v20
	v_fma_f32 v203, v230, v148, 0
	v_mfma_f32_16x16x32_bf16 v[12:15], v[70:73], v[192:195], v[12:15]
	v_max_i32_e32 v231, 0, v21
	v_fmac_f32_e32 v203, v231, v149
	v_max_i32_e32 v230, 0, v22
	s_waitcnt lgkmcnt(1)
	v_mfma_f32_16x16x32_bf16 v[0:3], v[58:61], v[196:199], v[0:3]
	v_fmac_f32_e32 v203, v230, v150
	v_max_i32_e32 v231, 0, v23
	v_fmac_f32_e32 v203, v231, v151
	v_mfma_f32_16x16x32_bf16 v[8:11], v[78:81], v[196:199], v[8:11]
	v_max_i32_e32 v230, 0, v28
	v_fmac_f32_e32 v203, v230, v152
	v_max_i32_e32 v231, 0, v29
	s_waitcnt lgkmcnt(0)
	v_mfma_f32_16x16x32_bf16 v[4:7], v[58:61], v[226:229], v[4:7]
	v_fmac_f32_e32 v203, v231, v153
	v_max_i32_e32 v230, 0, v30
	v_fmac_f32_e32 v203, v230, v154
	v_mfma_f32_16x16x32_bf16 v[12:15], v[78:81], v[226:229], v[12:15]
	v_max_i32_e32 v231, 0, v31
	v_fmac_f32_e32 v203, v231, v155
	v_mfma_f32_16x16x32_bf16 v[16:19], v[106:109], v[172:175], 0
	v_mfma_f32_16x16x32_bf16 v[24:27], v[94:97], v[172:175], 0
	ds_read_b128 v[172:175], v129 offset:16384
	v_mfma_f32_16x16x32_bf16 v[20:23], v[106:109], v[176:179], 0
	v_mfma_f32_16x16x32_bf16 v[28:31], v[94:97], v[176:179], 0
	ds_read_b128 v[176:179], v129 offset:16640
	v_mfma_f32_16x16x32_bf16 v[16:19], v[82:85], v[180:183], v[16:19]
	v_max_i32_e32 v224, 0, v0
	v_fma_f32 v218, v224, v140, 0
	v_mfma_f32_16x16x32_bf16 v[24:27], v[98:101], v[180:183], v[24:27]
	ds_read_b128 v[180:183], v129 offset:18432
	v_max_i32_e32 v225, 0, v1
	v_fmac_f32_e32 v218, v225, v141
	v_mfma_f32_16x16x32_bf16 v[20:23], v[82:85], v[184:187], v[20:23]
	v_max_i32_e32 v224, 0, v2
	v_fmac_f32_e32 v218, v224, v142
	v_max_i32_e32 v225, 0, v3
	v_mfma_f32_16x16x32_bf16 v[28:31], v[98:101], v[184:187], v[28:31]
	ds_read_b128 v[184:187], v129 offset:18688
	v_fmac_f32_e32 v218, v225, v143
	v_max_i32_e32 v224, 0, v8
	v_fmac_f32_e32 v218, v224, v144
	v_mfma_f32_16x16x32_bf16 v[16:19], v[86:89], v[188:191], v[16:19]
	v_max_i32_e32 v225, 0, v9
	v_fmac_f32_e32 v218, v225, v145
	v_max_i32_e32 v224, 0, v10
	v_mfma_f32_16x16x32_bf16 v[24:27], v[102:105], v[188:191], v[24:27]
	ds_read_b128 v[188:191], v129 offset:20480
	v_fmac_f32_e32 v218, v224, v146
	v_max_i32_e32 v225, 0, v11
	v_fmac_f32_e32 v218, v225, v147
	v_mfma_f32_16x16x32_bf16 v[20:23], v[86:89], v[192:195], v[20:23]
	v_max_i32_e32 v224, 0, v4
	v_fma_f32 v219, v224, v140, 0
	v_max_i32_e32 v225, 0, v5
	v_mfma_f32_16x16x32_bf16 v[28:31], v[102:105], v[192:195], v[28:31]
	ds_read_b128 v[192:195], v129 offset:20736
	v_fmac_f32_e32 v219, v225, v141
	v_max_i32_e32 v224, 0, v6
	v_fmac_f32_e32 v219, v224, v142
	v_mfma_f32_16x16x32_bf16 v[16:19], v[90:93], v[196:199], v[16:19]
	v_max_i32_e32 v225, 0, v7
	v_fmac_f32_e32 v219, v225, v143
	v_max_i32_e32 v224, 0, v12
	v_mfma_f32_16x16x32_bf16 v[24:27], v[110:113], v[196:199], v[24:27]
	ds_read_b128 v[196:199], v129 offset:22528
	v_fmac_f32_e32 v219, v224, v144
	v_max_i32_e32 v225, 0, v13
	v_fmac_f32_e32 v219, v225, v145
	v_mfma_f32_16x16x32_bf16 v[20:23], v[90:93], v[226:229], v[20:23]
	v_max_i32_e32 v224, 0, v14
	v_fmac_f32_e32 v219, v224, v146
	v_mfma_f32_16x16x32_bf16 v[28:31], v[110:113], v[226:229], v[28:31]
	ds_read_b128 v[226:229], v129 offset:22784
	v_max_i32_e32 v225, 0, v15
	v_fmac_f32_e32 v219, v225, v147
	s_waitcnt lgkmcnt(7)
; __device__ __forceinline__ void ph_indexer(const Params& p, char* shm) {
;     ...
;           IDX_TILE(ktp * 2, pr0);
;           __builtin_amdgcn_sched_barrier(0);
;           IDX_TILE(ktp * 2 + 1, pr1);
;           __builtin_amdgcn_sched_barrier(0);
;     ...
; #pragma unroll
;           for (int q = 0; q < 2; ++q) {
;             const float mine = half ? pr1[q] : pr0[q];
;             const float send = half ? pr0[q] : pr1[q];
;             const float recv = __shfl_xor(send, 32);
;             p.SC[(rowb + wid * 2 + q) * L + st * 128 + ktp * 64 + lane] = mine + recv;
;           }
	v_mfma_f32_16x16x32_bf16 v[0:3], v[74:77], v[172:175], 0
	v_mfma_f32_16x16x32_bf16 v[8:11], v[62:65], v[172:175], 0
	s_waitcnt lgkmcnt(6)
	v_mfma_f32_16x16x32_bf16 v[4:7], v[74:77], v[176:179], 0
	v_mfma_f32_16x16x32_bf16 v[12:15], v[62:65], v[176:179], 0
	v_max_i32_e32 v230, 0, v16
	v_fma_f32 v220, v230, v148, 0
	s_waitcnt lgkmcnt(5)
	v_mfma_f32_16x16x32_bf16 v[0:3], v[50:53], v[180:183], v[0:3]
	v_max_i32_e32 v231, 0, v17
	v_fmac_f32_e32 v220, v231, v149
	v_mfma_f32_16x16x32_bf16 v[8:11], v[66:69], v[180:183], v[8:11]
	v_max_i32_e32 v230, 0, v18
	v_fmac_f32_e32 v220, v230, v150
	s_waitcnt lgkmcnt(4)
	v_mfma_f32_16x16x32_bf16 v[4:7], v[50:53], v[184:187], v[4:7]
	v_max_i32_e32 v231, 0, v19
	v_fmac_f32_e32 v220, v231, v151
	v_mfma_f32_16x16x32_bf16 v[12:15], v[66:69], v[184:187], v[12:15]
	v_max_i32_e32 v230, 0, v24
	v_fmac_f32_e32 v220, v230, v152
	s_waitcnt lgkmcnt(3)
	v_mfma_f32_16x16x32_bf16 v[0:3], v[54:57], v[188:191], v[0:3]
	v_max_i32_e32 v231, 0, v25
	v_fmac_f32_e32 v220, v231, v153
	v_mfma_f32_16x16x32_bf16 v[8:11], v[70:73], v[188:191], v[8:11]
	v_max_i32_e32 v230, 0, v26
	v_fmac_f32_e32 v220, v230, v154
	v_max_i32_e32 v231, 0, v27
	s_waitcnt lgkmcnt(2)
	v_mfma_f32_16x16x32_bf16 v[4:7], v[54:57], v[192:195], v[4:7]
	v_fmac_f32_e32 v220, v231, v155
	v_max_i32_e32 v230, 0, v20
	v_fma_f32 v221, v230, v148, 0
	v_mfma_f32_16x16x32_bf16 v[12:15], v[70:73], v[192:195], v[12:15]
	v_max_i32_e32 v231, 0, v21
	v_fmac_f32_e32 v221, v231, v149
	v_max_i32_e32 v230, 0, v22
	s_waitcnt lgkmcnt(1)
	v_mfma_f32_16x16x32_bf16 v[0:3], v[58:61], v[196:199], v[0:3]
	v_fmac_f32_e32 v221, v230, v150
	v_max_i32_e32 v231, 0, v23
	v_fmac_f32_e32 v221, v231, v151
	v_mfma_f32_16x16x32_bf16 v[8:11], v[78:81], v[196:199], v[8:11]
	v_max_i32_e32 v230, 0, v28
	v_fmac_f32_e32 v221, v230, v152
	v_max_i32_e32 v231, 0, v29
	s_waitcnt lgkmcnt(0)
	v_mfma_f32_16x16x32_bf16 v[4:7], v[58:61], v[226:229], v[4:7]
	v_fmac_f32_e32 v221, v231, v153
	v_max_i32_e32 v230, 0, v30
	v_fmac_f32_e32 v221, v230, v154
	v_mfma_f32_16x16x32_bf16 v[12:15], v[78:81], v[226:229], v[12:15]
	v_max_i32_e32 v231, 0, v31
	v_fmac_f32_e32 v221, v231, v155
	v_mfma_f32_16x16x32_bf16 v[16:19], v[106:109], v[172:175], 0
	s_nop 1
	v_permlane16_swap_b32_e32 v200, v201
	v_permlane16_swap_b32_e32 v218, v219
	v_permlane16_swap_b32_e32 v202, v203
	v_mfma_f32_16x16x32_bf16 v[24:27], v[94:97], v[172:175], 0
	ds_read_b128 v[172:175], v129 offset:24576
	v_permlane16_swap_b32_e32 v220, v221
	v_add_f32_e32 v200, v200, v201
	v_add_f32_e32 v218, v218, v219
	v_add_f32_e32 v202, v202, v203
	v_mfma_f32_16x16x32_bf16 v[20:23], v[106:109], v[176:179], 0
	v_add_f32_e32 v220, v220, v221
	s_nop 1
	v_permlane32_swap_b32_e32 v200, v218
	v_permlane32_swap_b32_e32 v202, v220
	v_mfma_f32_16x16x32_bf16 v[28:31], v[94:97], v[176:179], 0
	ds_read_b128 v[176:179], v129 offset:24832
	v_add_f32_e32 v200, v200, v218
	v_add_f32_e32 v202, v202, v220
	global_store_dword v[232:233], v200, off
	global_store_dword v[234:235], v202, off
	v_mfma_f32_16x16x32_bf16 v[16:19], v[82:85], v[180:183], v[16:19]
	v_max_i32_e32 v224, 0, v0
	v_fma_f32 v222, v224, v140, 0
	v_mfma_f32_16x16x32_bf16 v[24:27], v[98:101], v[180:183], v[24:27]
	ds_read_b128 v[180:183], v129 offset:26624
	v_max_i32_e32 v225, 0, v1
	v_fmac_f32_e32 v222, v225, v141
	v_mfma_f32_16x16x32_bf16 v[20:23], v[82:85], v[184:187], v[20:23]
	v_max_i32_e32 v224, 0, v2
	v_fmac_f32_e32 v222, v224, v142
	v_max_i32_e32 v225, 0, v3
	v_mfma_f32_16x16x32_bf16 v[28:31], v[98:101], v[184:187], v[28:31]
	ds_read_b128 v[184:187], v129 offset:26880
	v_fmac_f32_e32 v222, v225, v143
	v_max_i32_e32 v224, 0, v8
	v_fmac_f32_e32 v222, v224, v144
	v_mfma_f32_16x16x32_bf16 v[16:19], v[86:89], v[188:191], v[16:19]
	v_max_i32_e32 v225, 0, v9
	v_fmac_f32_e32 v222, v225, v145
	v_max_i32_e32 v224, 0, v10
	v_mfma_f32_16x16x32_bf16 v[24:27], v[102:105], v[188:191], v[24:27]
	ds_read_b128 v[188:191], v129 offset:28672
	v_fmac_f32_e32 v222, v224, v146
	v_max_i32_e32 v225, 0, v11
	v_fmac_f32_e32 v222, v225, v147
	v_mfma_f32_16x16x32_bf16 v[20:23], v[86:89], v[192:195], v[20:23]
	v_max_i32_e32 v224, 0, v4
	v_fma_f32 v223, v224, v140, 0
	v_max_i32_e32 v225, 0, v5
	v_mfma_f32_16x16x32_bf16 v[28:31], v[102:105], v[192:195], v[28:31]
	ds_read_b128 v[192:195], v129 offset:28928
	v_fmac_f32_e32 v223, v225, v141
	v_max_i32_e32 v224, 0, v6
	v_fmac_f32_e32 v223, v224, v142
	v_mfma_f32_16x16x32_bf16 v[16:19], v[90:93], v[196:199], v[16:19]
	v_max_i32_e32 v225, 0, v7
	v_fmac_f32_e32 v223, v225, v143
	v_max_i32_e32 v224, 0, v12
	v_mfma_f32_16x16x32_bf16 v[24:27], v[110:113], v[196:199], v[24:27]
	ds_read_b128 v[196:199], v129 offset:30720
	v_fmac_f32_e32 v223, v224, v144
	v_max_i32_e32 v225, 0, v13
	v_fmac_f32_e32 v223, v225, v145
	v_mfma_f32_16x16x32_bf16 v[20:23], v[90:93], v[226:229], v[20:23]
	v_max_i32_e32 v224, 0, v14
	v_fmac_f32_e32 v223, v224, v146
	v_mfma_f32_16x16x32_bf16 v[28:31], v[110:113], v[226:229], v[28:31]
	ds_read_b128 v[226:229], v129 offset:30976
	v_max_i32_e32 v225, 0, v15
	v_fmac_f32_e32 v223, v225, v147
	s_waitcnt lgkmcnt(7)
	v_mfma_f32_16x16x32_bf16 v[0:3], v[74:77], v[172:175], 0
	v_mfma_f32_16x16x32_bf16 v[8:11], v[62:65], v[172:175], 0
	s_waitcnt lgkmcnt(6)
	v_mfma_f32_16x16x32_bf16 v[4:7], v[74:77], v[176:179], 0
	v_mfma_f32_16x16x32_bf16 v[12:15], v[62:65], v[176:179], 0
	v_max_i32_e32 v230, 0, v16
	v_fma_f32 v202, v230, v148, 0
	s_waitcnt lgkmcnt(5)
; __device__ __forceinline__ void ph_indexer(const Params& p, char* shm) {
;     ...
;           IDX_TILE(ktp * 2, pr0);
;           __builtin_amdgcn_sched_barrier(0);
;           IDX_TILE(ktp * 2 + 1, pr1);
;           __builtin_amdgcn_sched_barrier(0);
;     ...
; #pragma unroll
;           for (int q = 0; q < 2; ++q) {
;             const float mine = half ? pr1[q] : pr0[q];
;             const float send = half ? pr0[q] : pr1[q];
;             const float recv = __shfl_xor(send, 32);
;             p.SC[(rowb + wid * 2 + q) * L + st * 128 + ktp * 64 + lane] = mine + recv;
;           }
	v_mfma_f32_16x16x32_bf16 v[0:3], v[50:53], v[180:183], v[0:3]
	v_max_i32_e32 v231, 0, v17
	v_fmac_f32_e32 v202, v231, v149
	v_mfma_f32_16x16x32_bf16 v[8:11], v[66:69], v[180:183], v[8:11]
	v_max_i32_e32 v230, 0, v18
	v_fmac_f32_e32 v202, v230, v150
	s_waitcnt lgkmcnt(4)
	v_mfma_f32_16x16x32_bf16 v[4:7], v[50:53], v[184:187], v[4:7]
	v_max_i32_e32 v231, 0, v19
	v_fmac_f32_e32 v202, v231, v151
	v_mfma_f32_16x16x32_bf16 v[12:15], v[66:69], v[184:187], v[12:15]
	v_max_i32_e32 v230, 0, v24
	v_fmac_f32_e32 v202, v230, v152
	s_waitcnt lgkmcnt(3)
	v_mfma_f32_16x16x32_bf16 v[0:3], v[54:57], v[188:191], v[0:3]
	v_max_i32_e32 v231, 0, v25
	v_fmac_f32_e32 v202, v231, v153
	v_mfma_f32_16x16x32_bf16 v[8:11], v[70:73], v[188:191], v[8:11]
	v_max_i32_e32 v230, 0, v26
	v_fmac_f32_e32 v202, v230, v154
	v_max_i32_e32 v231, 0, v27
	s_waitcnt lgkmcnt(2)
	v_mfma_f32_16x16x32_bf16 v[4:7], v[54:57], v[192:195], v[4:7]
	v_fmac_f32_e32 v202, v231, v155
	v_max_i32_e32 v230, 0, v20
	v_fma_f32 v203, v230, v148, 0
	v_mfma_f32_16x16x32_bf16 v[12:15], v[70:73], v[192:195], v[12:15]
	v_max_i32_e32 v231, 0, v21
	v_fmac_f32_e32 v203, v231, v149
	v_max_i32_e32 v230, 0, v22
	s_waitcnt lgkmcnt(1)
	v_mfma_f32_16x16x32_bf16 v[0:3], v[58:61], v[196:199], v[0:3]
	v_fmac_f32_e32 v203, v230, v150
	v_max_i32_e32 v231, 0, v23
	v_fmac_f32_e32 v203, v231, v151
	v_mfma_f32_16x16x32_bf16 v[8:11], v[78:81], v[196:199], v[8:11]
	v_max_i32_e32 v230, 0, v28
	v_fmac_f32_e32 v203, v230, v152
	v_max_i32_e32 v231, 0, v29
	s_waitcnt lgkmcnt(0)
	v_mfma_f32_16x16x32_bf16 v[4:7], v[58:61], v[226:229], v[4:7]
	v_fmac_f32_e32 v203, v231, v153
	v_max_i32_e32 v230, 0, v30
	v_fmac_f32_e32 v203, v230, v154
	v_mfma_f32_16x16x32_bf16 v[12:15], v[78:81], v[226:229], v[12:15]
	v_max_i32_e32 v231, 0, v31
	v_fmac_f32_e32 v203, v231, v155
	v_mfma_f32_16x16x32_bf16 v[16:19], v[106:109], v[172:175], 0
	v_mfma_f32_16x16x32_bf16 v[24:27], v[94:97], v[172:175], 0
	v_mfma_f32_16x16x32_bf16 v[20:23], v[106:109], v[176:179], 0
	v_mfma_f32_16x16x32_bf16 v[28:31], v[94:97], v[176:179], 0
	v_mfma_f32_16x16x32_bf16 v[16:19], v[82:85], v[180:183], v[16:19]
	v_max_i32_e32 v224, 0, v0
	v_fma_f32 v218, v224, v140, 0
	v_mfma_f32_16x16x32_bf16 v[24:27], v[98:101], v[180:183], v[24:27]
	v_max_i32_e32 v225, 0, v1
	v_fmac_f32_e32 v218, v225, v141
	v_mfma_f32_16x16x32_bf16 v[20:23], v[82:85], v[184:187], v[20:23]
	v_max_i32_e32 v224, 0, v2
	v_fmac_f32_e32 v218, v224, v142
	v_max_i32_e32 v225, 0, v3
	v_mfma_f32_16x16x32_bf16 v[28:31], v[98:101], v[184:187], v[28:31]
	v_fmac_f32_e32 v218, v225, v143
	v_max_i32_e32 v224, 0, v8
	v_fmac_f32_e32 v218, v224, v144
	v_mfma_f32_16x16x32_bf16 v[16:19], v[86:89], v[188:191], v[16:19]
	v_max_i32_e32 v225, 0, v9
	v_fmac_f32_e32 v218, v225, v145
	v_max_i32_e32 v224, 0, v10
	v_mfma_f32_16x16x32_bf16 v[24:27], v[102:105], v[188:191], v[24:27]
	v_fmac_f32_e32 v218, v224, v146
	v_max_i32_e32 v225, 0, v11
	v_fmac_f32_e32 v218, v225, v147
	v_mfma_f32_16x16x32_bf16 v[20:23], v[86:89], v[192:195], v[20:23]
	v_max_i32_e32 v224, 0, v4
	v_fma_f32 v219, v224, v140, 0
	v_max_i32_e32 v225, 0, v5
	v_mfma_f32_16x16x32_bf16 v[28:31], v[102:105], v[192:195], v[28:31]
	v_fmac_f32_e32 v219, v225, v141
	v_max_i32_e32 v224, 0, v6
	v_fmac_f32_e32 v219, v224, v142
	v_mfma_f32_16x16x32_bf16 v[16:19], v[90:93], v[196:199], v[16:19]
	v_max_i32_e32 v225, 0, v7
	v_fmac_f32_e32 v219, v225, v143
	v_max_i32_e32 v224, 0, v12
	v_mfma_f32_16x16x32_bf16 v[24:27], v[110:113], v[196:199], v[24:27]
	v_fmac_f32_e32 v219, v224, v144
	v_max_i32_e32 v225, 0, v13
	v_fmac_f32_e32 v219, v225, v145
	v_mfma_f32_16x16x32_bf16 v[20:23], v[90:93], v[226:229], v[20:23]
	v_max_i32_e32 v224, 0, v14
	v_fmac_f32_e32 v219, v224, v146
	v_mfma_f32_16x16x32_bf16 v[28:31], v[110:113], v[226:229], v[28:31]
	v_max_i32_e32 v225, 0, v15
	v_fmac_f32_e32 v219, v225, v147
	v_max_i32_e32 v230, 0, v16
	v_fma_f32 v220, v230, v148, 0
	v_max_i32_e32 v231, 0, v17
	v_fmac_f32_e32 v220, v231, v149
	v_max_i32_e32 v230, 0, v18
	v_fmac_f32_e32 v220, v230, v150
	v_max_i32_e32 v231, 0, v19
	v_fmac_f32_e32 v220, v231, v151
	v_max_i32_e32 v230, 0, v24
	v_fmac_f32_e32 v220, v230, v152
	v_max_i32_e32 v231, 0, v25
	v_fmac_f32_e32 v220, v231, v153
	v_max_i32_e32 v230, 0, v26
	v_fmac_f32_e32 v220, v230, v154
	v_max_i32_e32 v231, 0, v27
	v_fmac_f32_e32 v220, v231, v155
	v_max_i32_e32 v230, 0, v20
	v_fma_f32 v221, v230, v148, 0
	v_max_i32_e32 v231, 0, v21
	v_fmac_f32_e32 v221, v231, v149
	v_max_i32_e32 v230, 0, v22
	v_fmac_f32_e32 v221, v230, v150
	v_max_i32_e32 v231, 0, v23
	v_fmac_f32_e32 v221, v231, v151
	v_max_i32_e32 v230, 0, v28
	v_fmac_f32_e32 v221, v230, v152
	v_max_i32_e32 v231, 0, v29
	v_fmac_f32_e32 v221, v231, v153
	v_max_i32_e32 v230, 0, v30
	v_fmac_f32_e32 v221, v230, v154
	v_max_i32_e32 v231, 0, v31
	v_fmac_f32_e32 v221, v231, v155
	s_nop 1
	v_permlane16_swap_b32_e32 v222, v223
	v_permlane16_swap_b32_e32 v218, v219
	v_permlane16_swap_b32_e32 v202, v203
	v_permlane16_swap_b32_e32 v220, v221
	v_add_f32_e32 v222, v222, v223
	v_add_f32_e32 v218, v218, v219
	v_add_f32_e32 v202, v202, v203
	v_add_f32_e32 v220, v220, v221
	s_nop 1
	v_permlane32_swap_b32_e32 v222, v218
	v_permlane32_swap_b32_e32 v202, v220
	v_add_f32_e32 v222, v222, v218
	v_add_f32_e32 v202, v202, v220
	global_store_dword v[232:233], v222, off offset:256
	global_store_dword v[234:235], v202, off offset:256
	s_cmp_lg_u32 s22, s44
	s_cbranch_scc0 .LBB0_932
	s_mov_b32 s4, s22
	s_branch .LBB0_920

; #define WAIT_V0() asm volatile("s_waitcnt vmcnt(0)" ::: "memory")
; #define WAIT_L0() asm volatile("s_waitcnt lgkmcnt(0)" ::: "memory")
; __device__ __forceinline__ void ph_indexer(const Params& p, char* shm) {
;     ...
;       for (int st = 0; st < nst; ++st) {
;         if (st == 0) WAIT_V0(); else asm volatile("s_waitcnt vmcnt(4)" ::: "memory");
;         WAIT_L0();
;         __builtin_amdgcn_s_barrier();
;         if (st + 1 < nst) IDX_STAGE((st + 1) & 1, st + 1);
;         if (st == 0) {
; #pragma unroll
;           for (int q = 0; q < 2; ++q)
; #pragma unroll
;             for (int i4 = 0; i4 < 4; ++i4) {
;               const uint2 u = *(const uint2*)(wtab + (wid * 2 + q) * 64 + (half * 4 + 8 * i4) * 2);
;               wq[q][2 * i4] = __builtin_bit_cast(h16x2, u.x);
;               wq[q][2 * i4 + 1] = __builtin_bit_cast(h16x2, u.y);
;             }
;         }
;         const char* kbuf = shm + (st & 1) * 32768;
; #pragma unroll 1
;         for (int ktp = 0; ktp < 2; ++ktp) {
;           float pr0[2], pr1[2];
;     ...
;           IDX_TILE(ktp * 2, pr0);
;           __builtin_amdgcn_sched_barrier(0);
;           IDX_TILE(ktp * 2 + 1, pr1);
.LBB0_939:
	s_waitcnt lgkmcnt(0)
	s_add_i32 s20, s4, 1
	s_cmp_ge_u32 s20, s22
	s_barrier
.LBB0_941:
	s_andn2_b64 vcc, exec, s[18:19]
	s_cbranch_vccnz .LBB0_943
	v_lshrrev_b32_e32 v0, 1, v204
	v_and_b32_e32 v0, 24, v0
	v_add_u32_e32 v0, s27, v0
	s_waitcnt vmcnt(0)
	ds_read2_b64 v[34:37], v0 offset1:4
	ds_read2_b64 v[38:41], v0 offset0:8 offset1:12
.LBB0_943:
	s_lshl_b32 s3, s4, 15
	s_and_b32 s3, s3, 0x8000
	s_lshl_b32 s4, s4, 7
	v_or_b32_e32 v112, s3, v117
	v_lshl_add_u64 v[110:111], s[4:5], 2, v[124:125]
	ds_read_b128 v[160:163], v112
	ds_read_b128 v[164:167], v112 offset:256
	ds_read_b128 v[168:171], v112 offset:2048
	ds_read_b128 v[172:175], v112 offset:2304
	ds_read_b128 v[176:179], v112 offset:4096
	ds_read_b128 v[106:109], v112 offset:4352
	ds_read_b128 v[102:105], v112 offset:6144
	ds_read_b128 v[98:101], v112 offset:6400
	v_lshl_add_u64 v[228:229], v[110:111], 0, s[14:15]
	v_lshl_add_u64 v[230:231], v[110:111], 0, s[16:17]
	s_waitcnt lgkmcnt(8)
	v_cvt_f32_f16_e32 v128, v34
	v_cvt_f32_f16_sdwa v129, v34 dst_sel:DWORD dst_unused:UNUSED_PAD src0_sel:WORD_1
	v_cvt_f32_f16_e32 v130, v35
	v_cvt_f32_f16_sdwa v131, v35 dst_sel:DWORD dst_unused:UNUSED_PAD src0_sel:WORD_1
	v_cvt_f32_f16_e32 v132, v36
	v_cvt_f32_f16_sdwa v133, v36 dst_sel:DWORD dst_unused:UNUSED_PAD src0_sel:WORD_1
	v_cvt_f32_f16_e32 v134, v37
	v_cvt_f32_f16_sdwa v135, v37 dst_sel:DWORD dst_unused:UNUSED_PAD src0_sel:WORD_1
	v_cvt_f32_f16_e32 v136, v38
	v_cvt_f32_f16_sdwa v137, v38 dst_sel:DWORD dst_unused:UNUSED_PAD src0_sel:WORD_1
	v_cvt_f32_f16_e32 v138, v39
	v_cvt_f32_f16_sdwa v139, v39 dst_sel:DWORD dst_unused:UNUSED_PAD src0_sel:WORD_1
	v_cvt_f32_f16_e32 v140, v40
	v_cvt_f32_f16_sdwa v141, v40 dst_sel:DWORD dst_unused:UNUSED_PAD src0_sel:WORD_1
	v_cvt_f32_f16_e32 v142, v41
	v_cvt_f32_f16_sdwa v143, v41 dst_sel:DWORD dst_unused:UNUSED_PAD src0_sel:WORD_1
	s_waitcnt lgkmcnt(7)
	v_mfma_f32_16x16x32_bf16 v[0:3], v[58:61], v[160:163], 0
	v_mfma_f32_16x16x32_bf16 v[8:11], v[28:31], v[160:163], 0
	s_waitcnt lgkmcnt(6)
	v_mfma_f32_16x16x32_bf16 v[4:7], v[58:61], v[164:167], 0
	v_mfma_f32_16x16x32_bf16 v[12:15], v[28:31], v[164:167], 0
	s_waitcnt lgkmcnt(5)
	v_mfma_f32_16x16x32_bf16 v[0:3], v[16:19], v[168:171], v[0:3]
	v_mfma_f32_16x16x32_bf16 v[8:11], v[50:53], v[168:171], v[8:11]
	s_waitcnt lgkmcnt(4)
	v_mfma_f32_16x16x32_bf16 v[4:7], v[16:19], v[172:175], v[4:7]
	v_mfma_f32_16x16x32_bf16 v[12:15], v[50:53], v[172:175], v[12:15]
	s_waitcnt lgkmcnt(3)
	v_mfma_f32_16x16x32_bf16 v[0:3], v[20:23], v[176:179], v[0:3]
	v_mfma_f32_16x16x32_bf16 v[8:11], v[54:57], v[176:179], v[8:11]
	s_waitcnt lgkmcnt(2)
	v_mfma_f32_16x16x32_bf16 v[4:7], v[20:23], v[106:109], v[4:7]
	v_mfma_f32_16x16x32_bf16 v[12:15], v[54:57], v[106:109], v[12:15]
	s_waitcnt lgkmcnt(1)
	v_mfma_f32_16x16x32_bf16 v[0:3], v[24:27], v[102:105], v[0:3]
	v_mfma_f32_16x16x32_bf16 v[8:11], v[62:65], v[102:105], v[8:11]
	s_waitcnt lgkmcnt(0)
	v_mfma_f32_16x16x32_bf16 v[4:7], v[24:27], v[98:101], v[4:7]
	v_mfma_f32_16x16x32_bf16 v[12:15], v[62:65], v[98:101], v[12:15]
	v_mfma_f32_16x16x32_bf16 v[184:187], v[90:93], v[160:163], 0
	v_mfma_f32_16x16x32_bf16 v[192:195], v[78:81], v[160:163], 0
	ds_read_b128 v[160:163], v112 offset:8192
	v_mfma_f32_16x16x32_bf16 v[188:191], v[90:93], v[164:167], 0
	s_cmp_ge_u32 s20, s22
	s_cbranch_scc1 .Lidx_nostage_s1_0
	v_lshl_add_u32 v236, s20, 7, v118
	v_ashrrev_i32_e32 v237, 31, v236
	s_lshl_b32 s3, s20, 15
	v_lshlrev_b64 v[236:237], 8, v[236:237]
	s_and_b32 s3, s3, 0x8000
	v_lshl_add_u64 v[236:237], v[126:127], 0, v[236:237]
	s_add_i32 s21, s26, s3
	s_mov_b32 s3, s5
	v_lshl_add_u64 v[238:239], v[236:237], 0, s[2:3]
	s_add_i32 m0, s21, s29
	s_mov_b32 s9, s5
	global_load_lds_dwordx4 v[238:239], off
.Lidx_nostage_s1_0:
	v_mfma_f32_16x16x32_bf16 v[196:199], v[78:81], v[164:167], 0
	ds_read_b128 v[164:167], v112 offset:8448
	s_cmp_ge_u32 s20, s22
	s_cbranch_scc1 .Lidx_nostage_s1_1
	v_lshl_add_u64 v[238:239], v[236:237], 0, s[8:9]
	s_add_i32 m0, s21, s31
	s_mov_b32 s11, s5
	global_load_lds_dwordx4 v[238:239], off
.Lidx_nostage_s1_1:
	v_mfma_f32_16x16x32_bf16 v[184:187], v[66:69], v[168:171], v[184:187]
	s_cmp_ge_u32 s20, s22
	s_cbranch_scc1 .Lidx_nostage_s1_2
	v_lshl_add_u64 v[238:239], v[236:237], 0, s[10:11]
	s_add_i32 m0, s21, s35
	s_mov_b32 s13, s5
	global_load_lds_dwordx4 v[238:239], off
.Lidx_nostage_s1_2:
	v_max_i32_e32 v224, 0, v0
	v_fma_f32 v200, v224, v128, 0
	v_mfma_f32_16x16x32_bf16 v[192:195], v[82:85], v[168:171], v[192:195]
	ds_read_b128 v[168:171], v112 offset:10240
	s_cmp_ge_u32 s20, s22
	s_cbranch_scc1 .Lidx_nostage_s1_3
	v_lshl_add_u64 v[236:237], v[236:237], 0, s[12:13]
	s_add_i32 m0, s21, s37
	s_nop 0
	global_load_lds_dwordx4 v[236:237], off
; __device__ __forceinline__ void ph_indexer(const Params& p, char* shm) {
;     ...
;           IDX_TILE(ktp * 2, pr0);
;           __builtin_amdgcn_sched_barrier(0);
;           IDX_TILE(ktp * 2 + 1, pr1);
;           __builtin_amdgcn_sched_barrier(0);
;     ...
; #pragma unroll
;           for (int q = 0; q < 2; ++q) {
;             const float mine = half ? pr1[q] : pr0[q];
;             const float send = half ? pr0[q] : pr1[q];
;             const float recv = __shfl_xor(send, 32);
;             p.SC[(rowb + wid * 2 + q) * L + st * 128 + ktp * 64 + lane] = mine + recv;
;           }
.Lidx_nostage_s1_3:
	v_max_i32_e32 v225, 0, v1
	v_fmac_f32_e32 v200, v225, v129
	v_mfma_f32_16x16x32_bf16 v[188:191], v[66:69], v[172:175], v[188:191]
	v_max_i32_e32 v224, 0, v2
	v_fmac_f32_e32 v200, v224, v130
	v_max_i32_e32 v225, 0, v3
	v_mfma_f32_16x16x32_bf16 v[196:199], v[82:85], v[172:175], v[196:199]
	ds_read_b128 v[172:175], v112 offset:10496
	v_fmac_f32_e32 v200, v225, v131
	v_max_i32_e32 v224, 0, v8
	v_fmac_f32_e32 v200, v224, v132
	v_mfma_f32_16x16x32_bf16 v[184:187], v[70:73], v[176:179], v[184:187]
	v_max_i32_e32 v225, 0, v9
	v_fmac_f32_e32 v200, v225, v133
	v_max_i32_e32 v224, 0, v10
	v_mfma_f32_16x16x32_bf16 v[192:195], v[86:89], v[176:179], v[192:195]
	ds_read_b128 v[176:179], v112 offset:12288
	v_fmac_f32_e32 v200, v224, v134
	v_max_i32_e32 v225, 0, v11
	v_fmac_f32_e32 v200, v225, v135
	v_mfma_f32_16x16x32_bf16 v[188:191], v[70:73], v[106:109], v[188:191]
	v_max_i32_e32 v224, 0, v4
	v_fma_f32 v201, v224, v128, 0
	v_max_i32_e32 v225, 0, v5
	v_mfma_f32_16x16x32_bf16 v[196:199], v[86:89], v[106:109], v[196:199]
	ds_read_b128 v[106:109], v112 offset:12544
	v_fmac_f32_e32 v201, v225, v129
	v_max_i32_e32 v224, 0, v6
	v_fmac_f32_e32 v201, v224, v130
	v_mfma_f32_16x16x32_bf16 v[184:187], v[74:77], v[102:105], v[184:187]
	v_max_i32_e32 v225, 0, v7
	v_fmac_f32_e32 v201, v225, v131
	v_max_i32_e32 v224, 0, v12
	v_mfma_f32_16x16x32_bf16 v[192:195], v[94:97], v[102:105], v[192:195]
	ds_read_b128 v[102:105], v112 offset:14336
	v_fmac_f32_e32 v201, v224, v132
	v_max_i32_e32 v225, 0, v13
	v_fmac_f32_e32 v201, v225, v133
	v_mfma_f32_16x16x32_bf16 v[188:191], v[74:77], v[98:101], v[188:191]
	v_max_i32_e32 v224, 0, v14
	v_fmac_f32_e32 v201, v224, v134
	v_mfma_f32_16x16x32_bf16 v[196:199], v[94:97], v[98:101], v[196:199]
	ds_read_b128 v[98:101], v112 offset:14592
	v_max_i32_e32 v225, 0, v15
	v_fmac_f32_e32 v201, v225, v135
	s_waitcnt lgkmcnt(7)
	v_mfma_f32_16x16x32_bf16 v[0:3], v[58:61], v[160:163], 0
	v_mfma_f32_16x16x32_bf16 v[8:11], v[28:31], v[160:163], 0
	s_waitcnt lgkmcnt(6)
	v_mfma_f32_16x16x32_bf16 v[4:7], v[58:61], v[164:167], 0
	v_mfma_f32_16x16x32_bf16 v[12:15], v[28:31], v[164:167], 0
	v_max_i32_e32 v226, 0, v184
	v_fma_f32 v202, v226, v136, 0
	s_waitcnt lgkmcnt(5)
	v_mfma_f32_16x16x32_bf16 v[0:3], v[16:19], v[168:171], v[0:3]
	v_max_i32_e32 v227, 0, v185
	v_fmac_f32_e32 v202, v227, v137
	v_mfma_f32_16x16x32_bf16 v[8:11], v[50:53], v[168:171], v[8:11]
	v_max_i32_e32 v226, 0, v186
	v_fmac_f32_e32 v202, v226, v138
	s_waitcnt lgkmcnt(4)
	v_mfma_f32_16x16x32_bf16 v[4:7], v[16:19], v[172:175], v[4:7]
	v_max_i32_e32 v227, 0, v187
	v_fmac_f32_e32 v202, v227, v139
	v_mfma_f32_16x16x32_bf16 v[12:15], v[50:53], v[172:175], v[12:15]
	v_max_i32_e32 v226, 0, v192
	v_fmac_f32_e32 v202, v226, v140
	s_waitcnt lgkmcnt(3)
	v_mfma_f32_16x16x32_bf16 v[0:3], v[20:23], v[176:179], v[0:3]
	v_max_i32_e32 v227, 0, v193
	v_fmac_f32_e32 v202, v227, v141
	v_mfma_f32_16x16x32_bf16 v[8:11], v[54:57], v[176:179], v[8:11]
	v_max_i32_e32 v226, 0, v194
	v_fmac_f32_e32 v202, v226, v142
	v_max_i32_e32 v227, 0, v195
	s_waitcnt lgkmcnt(2)
	v_mfma_f32_16x16x32_bf16 v[4:7], v[20:23], v[106:109], v[4:7]
	v_fmac_f32_e32 v202, v227, v143
	v_max_i32_e32 v226, 0, v188
	v_fma_f32 v203, v226, v136, 0
	v_mfma_f32_16x16x32_bf16 v[12:15], v[54:57], v[106:109], v[12:15]
	v_max_i32_e32 v227, 0, v189
	v_fmac_f32_e32 v203, v227, v137
	v_max_i32_e32 v226, 0, v190
	s_waitcnt lgkmcnt(1)
	v_mfma_f32_16x16x32_bf16 v[0:3], v[24:27], v[102:105], v[0:3]
	v_fmac_f32_e32 v203, v226, v138
	v_max_i32_e32 v227, 0, v191
	v_fmac_f32_e32 v203, v227, v139
	v_mfma_f32_16x16x32_bf16 v[8:11], v[62:65], v[102:105], v[8:11]
	v_max_i32_e32 v226, 0, v196
	v_fmac_f32_e32 v203, v226, v140
	v_max_i32_e32 v227, 0, v197
	s_waitcnt lgkmcnt(0)
	v_mfma_f32_16x16x32_bf16 v[4:7], v[24:27], v[98:101], v[4:7]
	v_fmac_f32_e32 v203, v227, v141
	v_max_i32_e32 v226, 0, v198
	v_fmac_f32_e32 v203, v226, v142
	v_mfma_f32_16x16x32_bf16 v[12:15], v[62:65], v[98:101], v[12:15]
	v_max_i32_e32 v227, 0, v199
	v_fmac_f32_e32 v203, v227, v143
	v_mfma_f32_16x16x32_bf16 v[184:187], v[90:93], v[160:163], 0
	v_mfma_f32_16x16x32_bf16 v[192:195], v[78:81], v[160:163], 0
	ds_read_b128 v[160:163], v112 offset:16384
	v_mfma_f32_16x16x32_bf16 v[188:191], v[90:93], v[164:167], 0
	v_mfma_f32_16x16x32_bf16 v[196:199], v[78:81], v[164:167], 0
	ds_read_b128 v[164:167], v112 offset:16640
	v_mfma_f32_16x16x32_bf16 v[184:187], v[66:69], v[168:171], v[184:187]
	v_max_i32_e32 v224, 0, v0
	v_fma_f32 v218, v224, v128, 0
	v_mfma_f32_16x16x32_bf16 v[192:195], v[82:85], v[168:171], v[192:195]
	ds_read_b128 v[168:171], v112 offset:18432
	v_max_i32_e32 v225, 0, v1
	v_fmac_f32_e32 v218, v225, v129
	v_mfma_f32_16x16x32_bf16 v[188:191], v[66:69], v[172:175], v[188:191]
	v_max_i32_e32 v224, 0, v2
	v_fmac_f32_e32 v218, v224, v130
	v_max_i32_e32 v225, 0, v3
	v_mfma_f32_16x16x32_bf16 v[196:199], v[82:85], v[172:175], v[196:199]
	ds_read_b128 v[172:175], v112 offset:18688
	v_fmac_f32_e32 v218, v225, v131
	v_max_i32_e32 v224, 0, v8
	v_fmac_f32_e32 v218, v224, v132
	v_mfma_f32_16x16x32_bf16 v[184:187], v[70:73], v[176:179], v[184:187]
	v_max_i32_e32 v225, 0, v9
	v_fmac_f32_e32 v218, v225, v133
	v_max_i32_e32 v224, 0, v10
	v_mfma_f32_16x16x32_bf16 v[192:195], v[86:89], v[176:179], v[192:195]
	ds_read_b128 v[176:179], v112 offset:20480
	v_fmac_f32_e32 v218, v224, v134
	v_max_i32_e32 v225, 0, v11
	v_fmac_f32_e32 v218, v225, v135
	v_mfma_f32_16x16x32_bf16 v[188:191], v[70:73], v[106:109], v[188:191]
	v_max_i32_e32 v224, 0, v4
	v_fma_f32 v219, v224, v128, 0
	v_max_i32_e32 v225, 0, v5
	v_mfma_f32_16x16x32_bf16 v[196:199], v[86:89], v[106:109], v[196:199]
	ds_read_b128 v[106:109], v112 offset:20736
	v_fmac_f32_e32 v219, v225, v129
	v_max_i32_e32 v224, 0, v6
	v_fmac_f32_e32 v219, v224, v130
	v_mfma_f32_16x16x32_bf16 v[184:187], v[74:77], v[102:105], v[184:187]
	v_max_i32_e32 v225, 0, v7
	v_fmac_f32_e32 v219, v225, v131
	v_max_i32_e32 v224, 0, v12
	v_mfma_f32_16x16x32_bf16 v[192:195], v[94:97], v[102:105], v[192:195]
	ds_read_b128 v[102:105], v112 offset:22528
	v_fmac_f32_e32 v219, v224, v132
	v_max_i32_e32 v225, 0, v13
	v_fmac_f32_e32 v219, v225, v133
	v_mfma_f32_16x16x32_bf16 v[188:191], v[74:77], v[98:101], v[188:191]
	v_max_i32_e32 v224, 0, v14
	v_fmac_f32_e32 v219, v224, v134
	v_mfma_f32_16x16x32_bf16 v[196:199], v[94:97], v[98:101], v[196:199]
	ds_read_b128 v[98:101], v112 offset:22784
	v_max_i32_e32 v225, 0, v15
	v_fmac_f32_e32 v219, v225, v135
	s_waitcnt lgkmcnt(7)
; __device__ __forceinline__ void ph_indexer(const Params& p, char* shm) {
;     ...
;           IDX_TILE(ktp * 2, pr0);
;           __builtin_amdgcn_sched_barrier(0);
;           IDX_TILE(ktp * 2 + 1, pr1);
;           __builtin_amdgcn_sched_barrier(0);
;     ...
; #pragma unroll
;           for (int q = 0; q < 2; ++q) {
;             const float mine = half ? pr1[q] : pr0[q];
;             const float send = half ? pr0[q] : pr1[q];
;             const float recv = __shfl_xor(send, 32);
;             p.SC[(rowb + wid * 2 + q) * L + st * 128 + ktp * 64 + lane] = mine + recv;
;           }
	v_mfma_f32_16x16x32_bf16 v[0:3], v[58:61], v[160:163], 0
	v_mfma_f32_16x16x32_bf16 v[8:11], v[28:31], v[160:163], 0
	s_waitcnt lgkmcnt(6)
	v_mfma_f32_16x16x32_bf16 v[4:7], v[58:61], v[164:167], 0
	v_mfma_f32_16x16x32_bf16 v[12:15], v[28:31], v[164:167], 0
	v_max_i32_e32 v226, 0, v184
	v_fma_f32 v220, v226, v136, 0
	s_waitcnt lgkmcnt(5)
	v_mfma_f32_16x16x32_bf16 v[0:3], v[16:19], v[168:171], v[0:3]
	v_max_i32_e32 v227, 0, v185
	v_fmac_f32_e32 v220, v227, v137
	v_mfma_f32_16x16x32_bf16 v[8:11], v[50:53], v[168:171], v[8:11]
	v_max_i32_e32 v226, 0, v186
	v_fmac_f32_e32 v220, v226, v138
	s_waitcnt lgkmcnt(4)
	v_mfma_f32_16x16x32_bf16 v[4:7], v[16:19], v[172:175], v[4:7]
	v_max_i32_e32 v227, 0, v187
	v_fmac_f32_e32 v220, v227, v139
	v_mfma_f32_16x16x32_bf16 v[12:15], v[50:53], v[172:175], v[12:15]
	v_max_i32_e32 v226, 0, v192
	v_fmac_f32_e32 v220, v226, v140
	s_waitcnt lgkmcnt(3)
	v_mfma_f32_16x16x32_bf16 v[0:3], v[20:23], v[176:179], v[0:3]
	v_max_i32_e32 v227, 0, v193
	v_fmac_f32_e32 v220, v227, v141
	v_mfma_f32_16x16x32_bf16 v[8:11], v[54:57], v[176:179], v[8:11]
	v_max_i32_e32 v226, 0, v194
	v_fmac_f32_e32 v220, v226, v142
	v_max_i32_e32 v227, 0, v195
	s_waitcnt lgkmcnt(2)
	v_mfma_f32_16x16x32_bf16 v[4:7], v[20:23], v[106:109], v[4:7]
	v_fmac_f32_e32 v220, v227, v143
	v_max_i32_e32 v226, 0, v188
	v_fma_f32 v221, v226, v136, 0
	v_mfma_f32_16x16x32_bf16 v[12:15], v[54:57], v[106:109], v[12:15]
	v_max_i32_e32 v227, 0, v189
	v_fmac_f32_e32 v221, v227, v137
	v_max_i32_e32 v226, 0, v190
	s_waitcnt lgkmcnt(1)
	v_mfma_f32_16x16x32_bf16 v[0:3], v[24:27], v[102:105], v[0:3]
	v_fmac_f32_e32 v221, v226, v138
	v_max_i32_e32 v227, 0, v191
	v_fmac_f32_e32 v221, v227, v139
	v_mfma_f32_16x16x32_bf16 v[8:11], v[62:65], v[102:105], v[8:11]
	v_max_i32_e32 v226, 0, v196
	v_fmac_f32_e32 v221, v226, v140
	v_max_i32_e32 v227, 0, v197
	s_waitcnt lgkmcnt(0)
	v_mfma_f32_16x16x32_bf16 v[4:7], v[24:27], v[98:101], v[4:7]
	v_fmac_f32_e32 v221, v227, v141
	v_max_i32_e32 v226, 0, v198
	v_fmac_f32_e32 v221, v226, v142
	v_mfma_f32_16x16x32_bf16 v[12:15], v[62:65], v[98:101], v[12:15]
	v_max_i32_e32 v227, 0, v199
	v_fmac_f32_e32 v221, v227, v143
	v_mfma_f32_16x16x32_bf16 v[184:187], v[90:93], v[160:163], 0
	s_nop 1
	v_permlane16_swap_b32_e32 v200, v201
	v_permlane16_swap_b32_e32 v218, v219
	v_permlane16_swap_b32_e32 v202, v203
	v_mfma_f32_16x16x32_bf16 v[192:195], v[78:81], v[160:163], 0
	ds_read_b128 v[160:163], v112 offset:24576
	v_permlane16_swap_b32_e32 v220, v221
	v_add_f32_e32 v200, v200, v201
	v_add_f32_e32 v218, v218, v219
	v_add_f32_e32 v202, v202, v203
	v_mfma_f32_16x16x32_bf16 v[188:191], v[90:93], v[164:167], 0
	v_add_f32_e32 v220, v220, v221
	s_nop 1
	v_permlane32_swap_b32_e32 v200, v218
	v_permlane32_swap_b32_e32 v202, v220
	v_mfma_f32_16x16x32_bf16 v[196:199], v[78:81], v[164:167], 0
	ds_read_b128 v[164:167], v112 offset:24832
	v_add_f32_e32 v200, v200, v218
	v_add_f32_e32 v202, v202, v220
	global_store_dword v[228:229], v200, off
	global_store_dword v[230:231], v202, off
	v_mfma_f32_16x16x32_bf16 v[184:187], v[66:69], v[168:171], v[184:187]
	v_max_i32_e32 v224, 0, v0
	v_fma_f32 v222, v224, v128, 0
	v_mfma_f32_16x16x32_bf16 v[192:195], v[82:85], v[168:171], v[192:195]
	ds_read_b128 v[168:171], v112 offset:26624
	v_max_i32_e32 v225, 0, v1
	v_fmac_f32_e32 v222, v225, v129
	v_mfma_f32_16x16x32_bf16 v[188:191], v[66:69], v[172:175], v[188:191]
	v_max_i32_e32 v224, 0, v2
	v_fmac_f32_e32 v222, v224, v130
	v_max_i32_e32 v225, 0, v3
	v_mfma_f32_16x16x32_bf16 v[196:199], v[82:85], v[172:175], v[196:199]
	ds_read_b128 v[172:175], v112 offset:26880
	v_fmac_f32_e32 v222, v225, v131
	v_max_i32_e32 v224, 0, v8
	v_fmac_f32_e32 v222, v224, v132
	v_mfma_f32_16x16x32_bf16 v[184:187], v[70:73], v[176:179], v[184:187]
	v_max_i32_e32 v225, 0, v9
	v_fmac_f32_e32 v222, v225, v133
	v_max_i32_e32 v224, 0, v10
	v_mfma_f32_16x16x32_bf16 v[192:195], v[86:89], v[176:179], v[192:195]
	ds_read_b128 v[176:179], v112 offset:28672
	v_fmac_f32_e32 v222, v224, v134
	v_max_i32_e32 v225, 0, v11
	v_fmac_f32_e32 v222, v225, v135
	v_mfma_f32_16x16x32_bf16 v[188:191], v[70:73], v[106:109], v[188:191]
	v_max_i32_e32 v224, 0, v4
	v_fma_f32 v223, v224, v128, 0
	v_max_i32_e32 v225, 0, v5
	v_mfma_f32_16x16x32_bf16 v[196:199], v[86:89], v[106:109], v[196:199]
	ds_read_b128 v[106:109], v112 offset:28928
	v_fmac_f32_e32 v223, v225, v129
	v_max_i32_e32 v224, 0, v6
	v_fmac_f32_e32 v223, v224, v130
	v_mfma_f32_16x16x32_bf16 v[184:187], v[74:77], v[102:105], v[184:187]
	v_max_i32_e32 v225, 0, v7
	v_fmac_f32_e32 v223, v225, v131
	v_max_i32_e32 v224, 0, v12
	v_mfma_f32_16x16x32_bf16 v[192:195], v[94:97], v[102:105], v[192:195]
	ds_read_b128 v[102:105], v112 offset:30720
	v_fmac_f32_e32 v223, v224, v132
	v_max_i32_e32 v225, 0, v13
	v_fmac_f32_e32 v223, v225, v133
	v_mfma_f32_16x16x32_bf16 v[188:191], v[74:77], v[98:101], v[188:191]
	v_max_i32_e32 v224, 0, v14
	v_fmac_f32_e32 v223, v224, v134
	v_mfma_f32_16x16x32_bf16 v[196:199], v[94:97], v[98:101], v[196:199]
	ds_read_b128 v[98:101], v112 offset:30976
	v_max_i32_e32 v225, 0, v15
	v_fmac_f32_e32 v223, v225, v135
	s_waitcnt lgkmcnt(7)
	v_mfma_f32_16x16x32_bf16 v[0:3], v[58:61], v[160:163], 0
	v_mfma_f32_16x16x32_bf16 v[8:11], v[28:31], v[160:163], 0
	s_waitcnt lgkmcnt(6)
	v_mfma_f32_16x16x32_bf16 v[4:7], v[58:61], v[164:167], 0
	v_mfma_f32_16x16x32_bf16 v[12:15], v[28:31], v[164:167], 0
	v_max_i32_e32 v226, 0, v184
	v_fma_f32 v202, v226, v136, 0
	s_waitcnt lgkmcnt(5)
; __device__ __forceinline__ void ph_indexer(const Params& p, char* shm) {
;     ...
;           IDX_TILE(ktp * 2, pr0);
;           __builtin_amdgcn_sched_barrier(0);
;           IDX_TILE(ktp * 2 + 1, pr1);
;           __builtin_amdgcn_sched_barrier(0);
;     ...
; #pragma unroll
;           for (int q = 0; q < 2; ++q) {
;             const float mine = half ? pr1[q] : pr0[q];
;             const float send = half ? pr0[q] : pr1[q];
;             const float recv = __shfl_xor(send, 32);
;             p.SC[(rowb + wid * 2 + q) * L + st * 128 + ktp * 64 + lane] = mine + recv;
;           }
	v_mfma_f32_16x16x32_bf16 v[0:3], v[16:19], v[168:171], v[0:3]
	v_max_i32_e32 v227, 0, v185
	v_fmac_f32_e32 v202, v227, v137
	v_mfma_f32_16x16x32_bf16 v[8:11], v[50:53], v[168:171], v[8:11]
	v_max_i32_e32 v226, 0, v186
	v_fmac_f32_e32 v202, v226, v138
	s_waitcnt lgkmcnt(4)
	v_mfma_f32_16x16x32_bf16 v[4:7], v[16:19], v[172:175], v[4:7]
	v_max_i32_e32 v227, 0, v187
	v_fmac_f32_e32 v202, v227, v139
	v_mfma_f32_16x16x32_bf16 v[12:15], v[50:53], v[172:175], v[12:15]
	v_max_i32_e32 v226, 0, v192
	v_fmac_f32_e32 v202, v226, v140
	s_waitcnt lgkmcnt(3)
	v_mfma_f32_16x16x32_bf16 v[0:3], v[20:23], v[176:179], v[0:3]
	v_max_i32_e32 v227, 0, v193
	v_fmac_f32_e32 v202, v227, v141
	v_mfma_f32_16x16x32_bf16 v[8:11], v[54:57], v[176:179], v[8:11]
	v_max_i32_e32 v226, 0, v194
	v_fmac_f32_e32 v202, v226, v142
	v_max_i32_e32 v227, 0, v195
	s_waitcnt lgkmcnt(2)
	v_mfma_f32_16x16x32_bf16 v[4:7], v[20:23], v[106:109], v[4:7]
	v_fmac_f32_e32 v202, v227, v143
	v_max_i32_e32 v226, 0, v188
	v_fma_f32 v203, v226, v136, 0
	v_mfma_f32_16x16x32_bf16 v[12:15], v[54:57], v[106:109], v[12:15]
	v_max_i32_e32 v227, 0, v189
	v_fmac_f32_e32 v203, v227, v137
	v_max_i32_e32 v226, 0, v190
	s_waitcnt lgkmcnt(1)
	v_mfma_f32_16x16x32_bf16 v[0:3], v[24:27], v[102:105], v[0:3]
	v_fmac_f32_e32 v203, v226, v138
	v_max_i32_e32 v227, 0, v191
	v_fmac_f32_e32 v203, v227, v139
	v_mfma_f32_16x16x32_bf16 v[8:11], v[62:65], v[102:105], v[8:11]
	v_max_i32_e32 v226, 0, v196
	v_fmac_f32_e32 v203, v226, v140
	v_max_i32_e32 v227, 0, v197
	s_waitcnt lgkmcnt(0)
	v_mfma_f32_16x16x32_bf16 v[4:7], v[24:27], v[98:101], v[4:7]
	v_fmac_f32_e32 v203, v227, v141
	v_max_i32_e32 v226, 0, v198
	v_fmac_f32_e32 v203, v226, v142
	v_mfma_f32_16x16x32_bf16 v[12:15], v[62:65], v[98:101], v[12:15]
	v_max_i32_e32 v227, 0, v199
	v_fmac_f32_e32 v203, v227, v143
	v_mfma_f32_16x16x32_bf16 v[184:187], v[90:93], v[160:163], 0
	v_mfma_f32_16x16x32_bf16 v[192:195], v[78:81], v[160:163], 0
	v_mfma_f32_16x16x32_bf16 v[188:191], v[90:93], v[164:167], 0
	v_mfma_f32_16x16x32_bf16 v[196:199], v[78:81], v[164:167], 0
	v_mfma_f32_16x16x32_bf16 v[184:187], v[66:69], v[168:171], v[184:187]
	v_max_i32_e32 v224, 0, v0
	v_fma_f32 v218, v224, v128, 0
	v_mfma_f32_16x16x32_bf16 v[192:195], v[82:85], v[168:171], v[192:195]
	v_max_i32_e32 v225, 0, v1
	v_fmac_f32_e32 v218, v225, v129
	v_mfma_f32_16x16x32_bf16 v[188:191], v[66:69], v[172:175], v[188:191]
	v_max_i32_e32 v224, 0, v2
	v_fmac_f32_e32 v218, v224, v130
	v_max_i32_e32 v225, 0, v3
	v_mfma_f32_16x16x32_bf16 v[196:199], v[82:85], v[172:175], v[196:199]
	v_fmac_f32_e32 v218, v225, v131
	v_max_i32_e32 v224, 0, v8
	v_fmac_f32_e32 v218, v224, v132
	v_mfma_f32_16x16x32_bf16 v[184:187], v[70:73], v[176:179], v[184:187]
	v_max_i32_e32 v225, 0, v9
	v_fmac_f32_e32 v218, v225, v133
	v_max_i32_e32 v224, 0, v10
	v_mfma_f32_16x16x32_bf16 v[192:195], v[86:89], v[176:179], v[192:195]
	v_fmac_f32_e32 v218, v224, v134
	v_max_i32_e32 v225, 0, v11
	v_fmac_f32_e32 v218, v225, v135
	v_mfma_f32_16x16x32_bf16 v[188:191], v[70:73], v[106:109], v[188:191]
	v_max_i32_e32 v224, 0, v4
	v_fma_f32 v219, v224, v128, 0
	v_max_i32_e32 v225, 0, v5
	v_mfma_f32_16x16x32_bf16 v[196:199], v[86:89], v[106:109], v[196:199]
	v_fmac_f32_e32 v219, v225, v129
	v_max_i32_e32 v224, 0, v6
	v_fmac_f32_e32 v219, v224, v130
	v_mfma_f32_16x16x32_bf16 v[184:187], v[74:77], v[102:105], v[184:187]
	v_max_i32_e32 v225, 0, v7
	v_fmac_f32_e32 v219, v225, v131
	v_max_i32_e32 v224, 0, v12
	v_mfma_f32_16x16x32_bf16 v[192:195], v[94:97], v[102:105], v[192:195]
	v_fmac_f32_e32 v219, v224, v132
	v_max_i32_e32 v225, 0, v13
	v_fmac_f32_e32 v219, v225, v133
	v_mfma_f32_16x16x32_bf16 v[188:191], v[74:77], v[98:101], v[188:191]
	v_max_i32_e32 v224, 0, v14
	v_fmac_f32_e32 v219, v224, v134
	v_mfma_f32_16x16x32_bf16 v[196:199], v[94:97], v[98:101], v[196:199]
	v_max_i32_e32 v225, 0, v15
	v_fmac_f32_e32 v219, v225, v135
	v_max_i32_e32 v226, 0, v184
	v_fma_f32 v220, v226, v136, 0
	v_max_i32_e32 v227, 0, v185
	v_fmac_f32_e32 v220, v227, v137
	v_max_i32_e32 v226, 0, v186
	v_fmac_f32_e32 v220, v226, v138
	v_max_i32_e32 v227, 0, v187
	v_fmac_f32_e32 v220, v227, v139
	v_max_i32_e32 v226, 0, v192
	v_fmac_f32_e32 v220, v226, v140
	v_max_i32_e32 v227, 0, v193
	v_fmac_f32_e32 v220, v227, v141
	v_max_i32_e32 v226, 0, v194
	v_fmac_f32_e32 v220, v226, v142
	v_max_i32_e32 v227, 0, v195
	v_fmac_f32_e32 v220, v227, v143
	v_max_i32_e32 v226, 0, v188
	v_fma_f32 v221, v226, v136, 0
	v_max_i32_e32 v227, 0, v189
	v_fmac_f32_e32 v221, v227, v137
	v_max_i32_e32 v226, 0, v190
	v_fmac_f32_e32 v221, v226, v138
	v_max_i32_e32 v227, 0, v191
	v_fmac_f32_e32 v221, v227, v139
	v_max_i32_e32 v226, 0, v196
	v_fmac_f32_e32 v221, v226, v140
	v_max_i32_e32 v227, 0, v197
	v_fmac_f32_e32 v221, v227, v141
	v_max_i32_e32 v226, 0, v198
	v_fmac_f32_e32 v221, v226, v142
	v_max_i32_e32 v227, 0, v199
	v_fmac_f32_e32 v221, v227, v143
	s_nop 1
	v_permlane16_swap_b32_e32 v222, v223
	v_permlane16_swap_b32_e32 v218, v219
	v_permlane16_swap_b32_e32 v202, v203
	v_permlane16_swap_b32_e32 v220, v221
	v_add_f32_e32 v222, v222, v223
	v_add_f32_e32 v218, v218, v219
	v_add_f32_e32 v202, v202, v203
	v_add_f32_e32 v220, v220, v221
	s_nop 1
	v_permlane32_swap_b32_e32 v222, v218
	v_permlane32_swap_b32_e32 v202, v220
	v_add_f32_e32 v222, v222, v218
	v_add_f32_e32 v202, v202, v220
	global_store_dword v[228:229], v222, off offset:256
	global_store_dword v[230:231], v202, off offset:256
	s_cmp_lg_u32 s20, s22
	s_cbranch_scc0 .LBB0_916
	s_mov_b32 s4, s20
	s_branch .LBB0_935

; __device__ __forceinline__ unsigned pack2(float a, float b) { const f32x2_t v = {a, b}; const bf16x2_t r = __builtin_convertvector(v, bf16x2_t); return __builtin_bit_cast(unsigned, r); }
; __device__ __forceinline__ void conv_transpose(const float* __restrict__ src, int ldsrc, u16* __restrict__ dst, int K, int ND, int mode, char* shm) {
;     ...
;   for (int t = blockIdx.x; t < nt; t += gridDim.x) {
;     const int tk = t / ntn, tn = t % ntn;
;     const int r = tid >> 6, c4 = tid & 63;
;     const int dn = tn * 256 + c4 * 4;
;     int sn = dn; bool z = false;
;     if (mode == 1) { if (dn >= 8960) sn = dn - 96; else if (dn >= 8864) z = true; }
;     float4 v[8];
; #pragma unroll
;     for (int i = 0; i < 8; ++i) {
;       v[i] = z ? float4{0.f, 0.f, 0.f, 0.f} : *(const float4*)(src + (size_t)(tk * 64 + r + 8 * i) * ldsrc + sn);
;     }
; #pragma unroll
;     for (int i = 0; i < 8; ++i) {
;       float* tp = tile + (r + 8 * i) * 257 + c4 * 4;
;       tp[0] = v[i].x; tp[1] = v[i].y; tp[2] = v[i].z; tp[3] = v[i].w;
;     }
;     __syncthreads();
; #pragma unroll
;     for (int i = 0; i < 4; ++i) {
;       const int item = tid + 512 * i, n = item >> 3, k8 = item & 7;
;       float f[8];
; #pragma unroll
;       for (int j = 0; j < 8; ++j) f[j] = tile[(k8 * 8 + j) * 257 + n];
;       uint4 o = {pack2(f[0], f[1]), pack2(f[2], f[3]), pack2(f[4], f[5]), pack2(f[6], f[7])};
;       *(uint4*)(dst + (size_t)(tn * 256 + n) * K + tk * 64 + k8 * 8) = o;
;     }
;     __syncthreads();
;   }
.LBB0_1772:
	s_ashr_i32 s8, s12, 31
	s_lshr_b32 s8, s8, 28
	s_add_i32 s8, s12, s8
	s_ashr_i32 s8, s8, 4
	s_lshl_b32 s9, s8, 12
	s_sub_i32 s13, s11, s9
	s_lshl_b32 s8, s8, 6
	v_add_u32_e32 v14, s13, v3
	v_add_u32_e32 v16, s8, v2
	v_ashrrev_i32_e32 v15, 31, v14
	v_ashrrev_i32_e32 v17, 31, v16
	v_lshl_add_u64 v[14:15], v[14:15], 2, s[0:1]
	v_lshlrev_b64 v[16:17], 14, v[16:17]
	v_lshl_add_u64 v[18:19], v[14:15], 0, v[16:17]
	global_load_dwordx4 v[60:63], v[18:19], off
	s_mov_b32 s9, 0xa0000
	s_add_i32 s12, s12, s4
	s_add_i32 s11, s11, s10
	v_add_co_u32_e32 v14, vcc, s14, v18
	s_nop 1
	v_addc_co_u32_e32 v15, vcc, 0, v19, vcc
	global_load_dwordx4 v[64:67], v[14:15], off
	v_add_co_u32_e32 v14, vcc, s16, v18
	s_nop 1
	v_addc_co_u32_e32 v15, vcc, 0, v19, vcc
	global_load_dwordx4 v[68:71], v[14:15], off
	v_add_co_u32_e32 v14, vcc, s17, v18
	s_nop 1
	v_addc_co_u32_e32 v15, vcc, 0, v19, vcc
	global_load_dwordx4 v[72:75], v[14:15], off
	v_add_co_u32_e32 v14, vcc, s18, v18
	s_nop 1
	v_addc_co_u32_e32 v15, vcc, 0, v19, vcc
	global_load_dwordx4 v[76:79], v[14:15], off
	v_add_co_u32_e32 v14, vcc, s9, v18
	s_nop 1
	v_addc_co_u32_e32 v15, vcc, 0, v19, vcc
	global_load_dwordx4 v[80:83], v[14:15], off
	s_mov_b32 s9, 0xc0000
	v_add_co_u32_e32 v14, vcc, s9, v18
	s_nop 1
	v_addc_co_u32_e32 v15, vcc, 0, v19, vcc
	global_load_dwordx4 v[84:87], v[14:15], off
	s_mov_b32 s9, 0xe0000
	v_add_co_u32_e32 v14, vcc, s9, v18
	s_nop 1
	v_addc_co_u32_e32 v15, vcc, 0, v19, vcc
	global_load_dwordx4 v[88:91], v[14:15], off
	s_ashr_i32 s9, s8, 31
	v_lshl_add_u64 v[18:19], s[8:9], 1, v[0:1]
	s_cmpk_lt_i32 s12, 0x400
	s_waitcnt vmcnt(7)
	ds_write2_b32 v8, v60, v61 offset1:1
	ds_write2_b32 v8, v62, v63 offset0:2 offset1:3
	s_waitcnt vmcnt(6)
	v_add_u32_e32 v13, 0x2020, v8
	ds_write2_b32 v13, v64, v65 offset1:1
	v_add_u32_e32 v13, 0x2028, v8
	ds_write2_b32 v13, v66, v67 offset1:1
	s_waitcnt vmcnt(5)
	v_add_u32_e32 v13, 0x4040, v8
	ds_write2_b32 v13, v68, v69 offset1:1
	v_add_u32_e32 v13, 0x4048, v8
	ds_write2_b32 v13, v70, v71 offset1:1
	s_waitcnt vmcnt(4)
	v_add_u32_e32 v13, 0x6060, v8
	ds_write2_b32 v13, v72, v73 offset1:1
	v_add_u32_e32 v13, 0x6068, v8
	ds_write2_b32 v13, v74, v75 offset1:1
	s_waitcnt vmcnt(3)
	v_add_u32_e32 v13, 0x8080, v8
	ds_write2_b32 v13, v76, v77 offset1:1
	v_add_u32_e32 v13, 0x8088, v8
	ds_write2_b32 v13, v78, v79 offset1:1
	s_waitcnt vmcnt(2)
	v_add_u32_e32 v13, 0xa0a0, v8
	ds_write2_b32 v13, v80, v81 offset1:1
	v_add_u32_e32 v13, 0xa0a8, v8
	ds_write2_b32 v13, v82, v83 offset1:1
	s_waitcnt vmcnt(1)
	v_add_u32_e32 v13, 0xc0c0, v8
	ds_write2_b32 v13, v84, v85 offset1:1
	v_add_u32_e32 v13, 0xc0c8, v8
	ds_write2_b32 v13, v86, v87 offset1:1
	s_waitcnt vmcnt(0)
	v_add_u32_e32 v13, 0xe0e0, v8
	ds_write2_b32 v13, v88, v89 offset1:1
	v_add_u32_e32 v13, 0xe0e8, v8
	ds_write2_b32 v13, v90, v91 offset1:1
	s_waitcnt lgkmcnt(0)
	s_barrier
	ds_read_b32 v13, v9
	ds_read_b32 v14, v9 offset:1028
	ds_read_b32 v15, v9 offset:2056
	ds_read_b32 v16, v9 offset:3084
	ds_read_b32 v17, v9 offset:4112
	ds_read_b32 v20, v9 offset:5140
	ds_read_b32 v21, v9 offset:6168
	ds_read_b32 v22, v9 offset:7196
	s_waitcnt lgkmcnt(4)
	v_cvt_pk_bf16_f32 v15, v15, v16
	v_cvt_pk_bf16_f32 v14, v13, v14
	s_waitcnt lgkmcnt(2)
	v_cvt_pk_bf16_f32 v16, v17, v20
	v_add_u32_e32 v20, s13, v5
	s_waitcnt lgkmcnt(0)
	v_cvt_pk_bf16_f32 v17, v21, v22
	v_ashrrev_i32_e32 v21, 31, v20
	v_lshlrev_b64 v[20:21], 13, v[20:21]
	v_lshl_add_u64 v[20:21], v[18:19], 0, v[20:21]
	global_store_dwordx4 v[20:21], v[14:17], off
	ds_read_b32 v13, v10
	ds_read_b32 v14, v10 offset:1028
	ds_read_b32 v15, v10 offset:2056
	ds_read_b32 v16, v10 offset:3084
	ds_read_b32 v17, v10 offset:4112
	ds_read_b32 v20, v10 offset:5140
	ds_read_b32 v21, v10 offset:6168
	ds_read_b32 v22, v10 offset:7196
	s_waitcnt lgkmcnt(4)
	v_cvt_pk_bf16_f32 v15, v15, v16
	v_cvt_pk_bf16_f32 v14, v13, v14
	s_waitcnt lgkmcnt(2)
	v_cvt_pk_bf16_f32 v16, v17, v20
	v_add_u32_e32 v20, s13, v6
	s_waitcnt lgkmcnt(0)
	v_cvt_pk_bf16_f32 v17, v21, v22
	v_ashrrev_i32_e32 v21, 31, v20
	v_lshlrev_b64 v[20:21], 13, v[20:21]
	v_lshl_add_u64 v[20:21], v[18:19], 0, v[20:21]
	global_store_dwordx4 v[20:21], v[14:17], off
	ds_read_b32 v13, v11
	ds_read_b32 v14, v11 offset:1028
	ds_read_b32 v15, v11 offset:2056
	ds_read_b32 v16, v11 offset:3084
	ds_read_b32 v17, v11 offset:4112
	ds_read_b32 v20, v11 offset:5140
	ds_read_b32 v21, v11 offset:6168
	ds_read_b32 v22, v11 offset:7196
	s_waitcnt lgkmcnt(4)
	v_cvt_pk_bf16_f32 v15, v15, v16
	v_cvt_pk_bf16_f32 v14, v13, v14
	s_waitcnt lgkmcnt(2)
	v_cvt_pk_bf16_f32 v16, v17, v20
	v_add_u32_e32 v20, s13, v7
	s_waitcnt lgkmcnt(0)
	v_cvt_pk_bf16_f32 v17, v21, v22
	v_ashrrev_i32_e32 v21, 31, v20
	v_lshlrev_b64 v[20:21], 13, v[20:21]
	v_lshl_add_u64 v[20:21], v[18:19], 0, v[20:21]
	global_store_dwordx4 v[20:21], v[14:17], off
	ds_read_b32 v13, v12
	ds_read_b32 v14, v12 offset:1028
	ds_read_b32 v15, v12 offset:2056
	ds_read_b32 v16, v12 offset:3084
	ds_read_b32 v17, v12 offset:4112
	ds_read_b32 v20, v12 offset:5140
	ds_read_b32 v21, v12 offset:6168
	ds_read_b32 v22, v12 offset:7196
	s_waitcnt lgkmcnt(4)
	v_cvt_pk_bf16_f32 v15, v15, v16
	v_cvt_pk_bf16_f32 v14, v13, v14
	s_waitcnt lgkmcnt(2)
	v_cvt_pk_bf16_f32 v16, v17, v20
	v_add_u32_e32 v20, s13, v4
	s_waitcnt lgkmcnt(0)
	v_cvt_pk_bf16_f32 v17, v21, v22
	v_ashrrev_i32_e32 v21, 31, v20
	v_lshlrev_b64 v[20:21], 13, v[20:21]
	v_lshl_add_u64 v[18:19], v[18:19], 0, v[20:21]
	global_store_dwordx4 v[18:19], v[14:17], off
	s_barrier
	s_cbranch_scc1 .LBB0_1772

; __device__ __forceinline__ unsigned pack2(float a, float b) { const f32x2_t v = {a, b}; const bf16x2_t r = __builtin_convertvector(v, bf16x2_t); return __builtin_bit_cast(unsigned, r); }
; __device__ __forceinline__ void conv_transpose(const float* __restrict__ src, int ldsrc, u16* __restrict__ dst, int K, int ND, int mode, char* shm) {
;     ...
;   for (int t = blockIdx.x; t < nt; t += gridDim.x) {
;     const int tk = t / ntn, tn = t % ntn;
;     const int r = tid >> 6, c4 = tid & 63;
;     const int dn = tn * 256 + c4 * 4;
;     int sn = dn; bool z = false;
;     if (mode == 1) { if (dn >= 8960) sn = dn - 96; else if (dn >= 8864) z = true; }
;     float4 v[8];
; #pragma unroll
;     for (int i = 0; i < 8; ++i) {
;       v[i] = z ? float4{0.f, 0.f, 0.f, 0.f} : *(const float4*)(src + (size_t)(tk * 64 + r + 8 * i) * ldsrc + sn);
;     }
; #pragma unroll
;     for (int i = 0; i < 8; ++i) {
;       float* tp = tile + (r + 8 * i) * 257 + c4 * 4;
;       tp[0] = v[i].x; tp[1] = v[i].y; tp[2] = v[i].z; tp[3] = v[i].w;
;     }
;     __syncthreads();
; #pragma unroll
;     for (int i = 0; i < 4; ++i) {
;       const int item = tid + 512 * i, n = item >> 3, k8 = item & 7;
;       float f[8];
; #pragma unroll
;       for (int j = 0; j < 8; ++j) f[j] = tile[(k8 * 8 + j) * 257 + n];
;       uint4 o = {pack2(f[0], f[1]), pack2(f[2], f[3]), pack2(f[4], f[5]), pack2(f[6], f[7])};
;       *(uint4*)(dst + (size_t)(tn * 256 + n) * K + tk * 64 + k8 * 8) = o;
;     }
;     __syncthreads();
;   }
.LBB0_1775:
	s_ashr_i32 s6, s10, 31
	s_lshr_b32 s6, s6, 29
	s_add_i32 s6, s10, s6
	s_ashr_i32 s6, s6, 3
	s_lshl_b32 s7, s6, 11
	s_sub_i32 s11, s9, s7
	s_lshl_b32 s6, s6, 6
	v_add_u32_e32 v14, s11, v3
	v_add_u32_e32 v16, s6, v2
	v_ashrrev_i32_e32 v15, 31, v14
	v_ashrrev_i32_e32 v17, 31, v16
	v_lshl_add_u64 v[14:15], v[14:15], 2, s[0:1]
	v_lshlrev_b64 v[16:17], 13, v[16:17]
	v_lshl_add_u64 v[18:19], v[14:15], 0, v[16:17]
	global_load_dwordx4 v[60:63], v[18:19], off
	s_mov_b32 s7, 0x30000
	s_add_i32 s10, s10, s4
	s_add_i32 s9, s9, s8
	v_add_co_u32_e32 v14, vcc, s12, v18
	s_nop 1
	v_addc_co_u32_e32 v15, vcc, 0, v19, vcc
	global_load_dwordx4 v[64:67], v[14:15], off
	v_add_co_u32_e32 v14, vcc, s13, v18
	s_nop 1
	v_addc_co_u32_e32 v15, vcc, 0, v19, vcc
	global_load_dwordx4 v[68:71], v[14:15], off
	v_add_co_u32_e32 v14, vcc, s7, v18
	s_nop 1
	v_addc_co_u32_e32 v15, vcc, 0, v19, vcc
	global_load_dwordx4 v[72:75], v[14:15], off
	s_mov_b32 s7, 0x50000
	v_add_co_u32_e32 v14, vcc, s14, v18
	s_nop 1
	v_addc_co_u32_e32 v15, vcc, 0, v19, vcc
	global_load_dwordx4 v[76:79], v[14:15], off
	v_add_co_u32_e32 v14, vcc, s7, v18
	s_nop 1
	v_addc_co_u32_e32 v15, vcc, 0, v19, vcc
	global_load_dwordx4 v[80:83], v[14:15], off
	s_mov_b32 s7, 0x70000
	v_add_co_u32_e32 v14, vcc, s16, v18
	s_nop 1
	v_addc_co_u32_e32 v15, vcc, 0, v19, vcc
	global_load_dwordx4 v[84:87], v[14:15], off
	v_add_co_u32_e32 v14, vcc, s7, v18
	s_nop 1
	v_addc_co_u32_e32 v15, vcc, 0, v19, vcc
	global_load_dwordx4 v[88:91], v[14:15], off
	s_ashr_i32 s7, s6, 31
	v_lshl_add_u64 v[18:19], s[6:7], 1, v[0:1]
	s_cmp_lt_i32 s10, 64
	s_waitcnt vmcnt(7)
	ds_write2_b32 v8, v60, v61 offset1:1
	ds_write2_b32 v8, v62, v63 offset0:2 offset1:3
	s_waitcnt vmcnt(6)
	v_add_u32_e32 v13, 0x2020, v8
	ds_write2_b32 v13, v64, v65 offset1:1
	v_add_u32_e32 v13, 0x2028, v8
	ds_write2_b32 v13, v66, v67 offset1:1
	s_waitcnt vmcnt(5)
	v_add_u32_e32 v13, 0x4040, v8
	ds_write2_b32 v13, v68, v69 offset1:1
	v_add_u32_e32 v13, 0x4048, v8
	ds_write2_b32 v13, v70, v71 offset1:1
	s_waitcnt vmcnt(4)
	v_add_u32_e32 v13, 0x6060, v8
	ds_write2_b32 v13, v72, v73 offset1:1
	v_add_u32_e32 v13, 0x6068, v8
	ds_write2_b32 v13, v74, v75 offset1:1
	s_waitcnt vmcnt(3)
	v_add_u32_e32 v13, 0x8080, v8
	ds_write2_b32 v13, v76, v77 offset1:1
	v_add_u32_e32 v13, 0x8088, v8
	ds_write2_b32 v13, v78, v79 offset1:1
	s_waitcnt vmcnt(2)
	v_add_u32_e32 v13, 0xa0a0, v8
	ds_write2_b32 v13, v80, v81 offset1:1
	v_add_u32_e32 v13, 0xa0a8, v8
	ds_write2_b32 v13, v82, v83 offset1:1
	s_waitcnt vmcnt(1)
	v_add_u32_e32 v13, 0xc0c0, v8
	ds_write2_b32 v13, v84, v85 offset1:1
	v_add_u32_e32 v13, 0xc0c8, v8
	ds_write2_b32 v13, v86, v87 offset1:1
	s_waitcnt vmcnt(0)
	v_add_u32_e32 v13, 0xe0e0, v8
	ds_write2_b32 v13, v88, v89 offset1:1
	v_add_u32_e32 v13, 0xe0e8, v8
	ds_write2_b32 v13, v90, v91 offset1:1
	s_waitcnt lgkmcnt(0)
	s_barrier
	ds_read_b32 v13, v9
	ds_read_b32 v14, v9 offset:1028
	ds_read_b32 v15, v9 offset:2056
	ds_read_b32 v16, v9 offset:3084
	ds_read_b32 v17, v9 offset:4112
	ds_read_b32 v20, v9 offset:5140
	ds_read_b32 v21, v9 offset:6168
	ds_read_b32 v22, v9 offset:7196
	s_waitcnt lgkmcnt(4)
	v_cvt_pk_bf16_f32 v15, v15, v16
	v_cvt_pk_bf16_f32 v14, v13, v14
	s_waitcnt lgkmcnt(2)
	v_cvt_pk_bf16_f32 v16, v17, v20
	v_add_u32_e32 v20, s11, v5
	s_waitcnt lgkmcnt(0)
	v_cvt_pk_bf16_f32 v17, v21, v22
	v_ashrrev_i32_e32 v21, 31, v20
	v_lshlrev_b64 v[20:21], 10, v[20:21]
	v_lshl_add_u64 v[20:21], v[18:19], 0, v[20:21]
	global_store_dwordx4 v[20:21], v[14:17], off
	ds_read_b32 v13, v10
	ds_read_b32 v14, v10 offset:1028
	ds_read_b32 v15, v10 offset:2056
	ds_read_b32 v16, v10 offset:3084
	ds_read_b32 v17, v10 offset:4112
	ds_read_b32 v20, v10 offset:5140
	ds_read_b32 v21, v10 offset:6168
	ds_read_b32 v22, v10 offset:7196
	s_waitcnt lgkmcnt(4)
	v_cvt_pk_bf16_f32 v15, v15, v16
	v_cvt_pk_bf16_f32 v14, v13, v14
	s_waitcnt lgkmcnt(2)
	v_cvt_pk_bf16_f32 v16, v17, v20
	v_add_u32_e32 v20, s11, v6
	s_waitcnt lgkmcnt(0)
	v_cvt_pk_bf16_f32 v17, v21, v22
	v_ashrrev_i32_e32 v21, 31, v20
	v_lshlrev_b64 v[20:21], 10, v[20:21]
	v_lshl_add_u64 v[20:21], v[18:19], 0, v[20:21]
	global_store_dwordx4 v[20:21], v[14:17], off
	ds_read_b32 v13, v11
	ds_read_b32 v14, v11 offset:1028
	ds_read_b32 v15, v11 offset:2056
	ds_read_b32 v16, v11 offset:3084
	ds_read_b32 v17, v11 offset:4112
	ds_read_b32 v20, v11 offset:5140
	ds_read_b32 v21, v11 offset:6168
	ds_read_b32 v22, v11 offset:7196
	s_waitcnt lgkmcnt(4)
	v_cvt_pk_bf16_f32 v15, v15, v16
	v_cvt_pk_bf16_f32 v14, v13, v14
	s_waitcnt lgkmcnt(2)
	v_cvt_pk_bf16_f32 v16, v17, v20
	v_add_u32_e32 v20, s11, v7
	s_waitcnt lgkmcnt(0)
	v_cvt_pk_bf16_f32 v17, v21, v22
	v_ashrrev_i32_e32 v21, 31, v20
	v_lshlrev_b64 v[20:21], 10, v[20:21]
	v_lshl_add_u64 v[20:21], v[18:19], 0, v[20:21]
	global_store_dwordx4 v[20:21], v[14:17], off
	ds_read_b32 v13, v12
	ds_read_b32 v14, v12 offset:1028
	ds_read_b32 v15, v12 offset:2056
	ds_read_b32 v16, v12 offset:3084
	ds_read_b32 v17, v12 offset:4112
	ds_read_b32 v20, v12 offset:5140
	ds_read_b32 v21, v12 offset:6168
	ds_read_b32 v22, v12 offset:7196
	s_waitcnt lgkmcnt(4)
	v_cvt_pk_bf16_f32 v15, v15, v16
	v_cvt_pk_bf16_f32 v14, v13, v14
	s_waitcnt lgkmcnt(2)
	v_cvt_pk_bf16_f32 v16, v17, v20
	v_add_u32_e32 v20, s11, v4
	s_waitcnt lgkmcnt(0)
	v_cvt_pk_bf16_f32 v17, v21, v22
	v_ashrrev_i32_e32 v21, 31, v20
	v_lshlrev_b64 v[20:21], 10, v[20:21]
	v_lshl_add_u64 v[18:19], v[18:19], 0, v[20:21]
	global_store_dwordx4 v[18:19], v[14:17], off
	s_barrier
	s_cbranch_scc1 .LBB0_1775
	s_branch .LBB0_1750
